# phase C + decode tile residual epilogues batched; phase A epilogue rowss prefetched
# speedup vs baseline: 1.1543x; 1.0124x over previous
.LBB0_244:
	v_lshrrev_b32_e32 v170, 5, v74
	v_mul_u32_u24_e32 v171, 0x210, v170
	v_lshl_add_u32 v171, v75, 4, v171
	v_add_u32_e32 v172, 0x10800, v171
	v_add_u32_e32 v173, 0x4000, v170
	v_lshlrev_b32_e32 v174, 10, v173
	v_add_u32_e32 v174, s53, v174
	v_lshl_add_u32 v174, v75, 2, v174
	v_lshlrev_b32_e32 v174, 2, v174
	v_lshlrev_b32_e32 v175, 2, v173
	v_xor_b32_e32 v176, 16, v192
	v_lshlrev_b32_e32 v176, 2, v176
	s_add_u32 s20, s94, 0x2500000
	s_addc_u32 s21, s95, 0
	s_and_b64 vcc, exec, s[44:45]
	s_cbranch_vccz .Lcepi_last_b3
	ds_read_b128 v[12:15], v171 offset:0
	v_mov_b32_e32 v134, v174
	global_load_dwordx4 v[100:103], v134, s[92:93]
	ds_read_b128 v[16:19], v171 offset:8448
	v_add_u32_e32 v135, 0x10000, v174
	global_load_dwordx4 v[104:107], v135, s[92:93]
	ds_read_b128 v[20:23], v171 offset:16896
	v_add_u32_e32 v136, 0x20000, v174
	global_load_dwordx4 v[108:111], v136, s[92:93]
	ds_read_b128 v[24:27], v171 offset:25344
	v_add_u32_e32 v137, 0x30000, v174
	global_load_dwordx4 v[112:115], v137, s[92:93]
	ds_read_b128 v[28:31], v171 offset:33792
	v_add_u32_e32 v138, 0x40000, v174
	global_load_dwordx4 v[116:119], v138, s[92:93]
	ds_read_b128 v[32:35], v171 offset:42240
	v_add_u32_e32 v139, 0x50000, v174
	global_load_dwordx4 v[120:123], v139, s[92:93]
	ds_read_b128 v[36:39], v171 offset:50688
	v_add_u32_e32 v140, 0x60000, v174
	global_load_dwordx4 v[124:127], v140, s[92:93]
	ds_read_b128 v[40:43], v171 offset:59136
	v_add_u32_e32 v141, 0x70000, v174
	global_load_dwordx4 v[128:131], v141, s[92:93]
	s_waitcnt vmcnt(7) lgkmcnt(7)
	v_pk_add_f32 v[100:101], v[100:101], v[12:13]
	v_pk_add_f32 v[102:103], v[102:103], v[14:15]
	global_store_dwordx4 v134, v[100:103], s[92:93]
	v_cvt_pk_bf16_f32 v12, v100, v101
	v_cvt_pk_bf16_f32 v13, v102, v103
	v_lshrrev_b32_e32 v14, 1, v134
	v_pk_mul_f32 v[100:101], v[100:101], v[100:101]
	v_pk_mul_f32 v[102:103], v[102:103], v[102:103]
	global_store_dwordx2 v14, v[12:13], s[20:21]
	v_add_f32_e32 v100, v100, v101
	v_add_f32_e32 v102, v102, v103
	v_add_f32_e32 v142, v100, v102
	s_waitcnt vmcnt(8) lgkmcnt(6)
	v_pk_add_f32 v[104:105], v[104:105], v[16:17]
	v_pk_add_f32 v[106:107], v[106:107], v[18:19]
	global_store_dwordx4 v135, v[104:107], s[92:93]
	v_cvt_pk_bf16_f32 v16, v104, v105
	v_cvt_pk_bf16_f32 v17, v106, v107
	v_lshrrev_b32_e32 v18, 1, v135
	v_pk_mul_f32 v[104:105], v[104:105], v[104:105]
	v_pk_mul_f32 v[106:107], v[106:107], v[106:107]
	global_store_dwordx2 v18, v[16:17], s[20:21]
	v_add_f32_e32 v104, v104, v105
	v_add_f32_e32 v106, v106, v107
	v_add_f32_e32 v143, v104, v106
	s_waitcnt vmcnt(9) lgkmcnt(5)
	v_pk_add_f32 v[108:109], v[108:109], v[20:21]
	v_pk_add_f32 v[110:111], v[110:111], v[22:23]
	global_store_dwordx4 v136, v[108:111], s[92:93]
	v_cvt_pk_bf16_f32 v20, v108, v109
	v_cvt_pk_bf16_f32 v21, v110, v111
	v_lshrrev_b32_e32 v22, 1, v136
	v_pk_mul_f32 v[108:109], v[108:109], v[108:109]
	v_pk_mul_f32 v[110:111], v[110:111], v[110:111]
	global_store_dwordx2 v22, v[20:21], s[20:21]
	v_add_f32_e32 v108, v108, v109
	v_add_f32_e32 v110, v110, v111
	v_add_f32_e32 v144, v108, v110
	s_waitcnt vmcnt(10) lgkmcnt(4)
	v_pk_add_f32 v[112:113], v[112:113], v[24:25]
	v_pk_add_f32 v[114:115], v[114:115], v[26:27]
	global_store_dwordx4 v137, v[112:115], s[92:93]
	v_cvt_pk_bf16_f32 v24, v112, v113
	v_cvt_pk_bf16_f32 v25, v114, v115
	v_lshrrev_b32_e32 v26, 1, v137
	v_pk_mul_f32 v[112:113], v[112:113], v[112:113]
	v_pk_mul_f32 v[114:115], v[114:115], v[114:115]
	global_store_dwordx2 v26, v[24:25], s[20:21]
	v_add_f32_e32 v112, v112, v113
	v_add_f32_e32 v114, v114, v115
	v_add_f32_e32 v145, v112, v114
	s_waitcnt vmcnt(11) lgkmcnt(3)
	v_pk_add_f32 v[116:117], v[116:117], v[28:29]
	v_pk_add_f32 v[118:119], v[118:119], v[30:31]
	global_store_dwordx4 v138, v[116:119], s[92:93]
	v_cvt_pk_bf16_f32 v28, v116, v117
	v_cvt_pk_bf16_f32 v29, v118, v119
	v_lshrrev_b32_e32 v30, 1, v138
	v_pk_mul_f32 v[116:117], v[116:117], v[116:117]
	v_pk_mul_f32 v[118:119], v[118:119], v[118:119]
	global_store_dwordx2 v30, v[28:29], s[20:21]
	v_add_f32_e32 v116, v116, v117
	v_add_f32_e32 v118, v118, v119
	v_add_f32_e32 v146, v116, v118
	s_waitcnt vmcnt(12) lgkmcnt(2)
	v_pk_add_f32 v[120:121], v[120:121], v[32:33]
	v_pk_add_f32 v[122:123], v[122:123], v[34:35]
	global_store_dwordx4 v139, v[120:123], s[92:93]
	v_cvt_pk_bf16_f32 v32, v120, v121
	v_cvt_pk_bf16_f32 v33, v122, v123
	v_lshrrev_b32_e32 v34, 1, v139
	v_pk_mul_f32 v[120:121], v[120:121], v[120:121]
	v_pk_mul_f32 v[122:123], v[122:123], v[122:123]
	global_store_dwordx2 v34, v[32:33], s[20:21]
	v_add_f32_e32 v120, v120, v121
	v_add_f32_e32 v122, v122, v123
	v_add_f32_e32 v147, v120, v122
	s_waitcnt vmcnt(13) lgkmcnt(1)
	v_pk_add_f32 v[124:125], v[124:125], v[36:37]
	v_pk_add_f32 v[126:127], v[126:127], v[38:39]
	global_store_dwordx4 v140, v[124:127], s[92:93]
	v_cvt_pk_bf16_f32 v36, v124, v125
	v_cvt_pk_bf16_f32 v37, v126, v127
	v_lshrrev_b32_e32 v38, 1, v140
	v_pk_mul_f32 v[124:125], v[124:125], v[124:125]
	v_pk_mul_f32 v[126:127], v[126:127], v[126:127]
	global_store_dwordx2 v38, v[36:37], s[20:21]
	v_add_f32_e32 v124, v124, v125
	v_add_f32_e32 v126, v126, v127
	v_add_f32_e32 v148, v124, v126
	s_waitcnt vmcnt(14) lgkmcnt(0)
	v_pk_add_f32 v[128:129], v[128:129], v[40:41]
	v_pk_add_f32 v[130:131], v[130:131], v[42:43]
	global_store_dwordx4 v141, v[128:131], s[92:93]
	v_cvt_pk_bf16_f32 v40, v128, v129
	v_cvt_pk_bf16_f32 v41, v130, v131
	v_lshrrev_b32_e32 v42, 1, v141
	v_pk_mul_f32 v[128:129], v[128:129], v[128:129]
	v_pk_mul_f32 v[130:131], v[130:131], v[130:131]
	global_store_dwordx2 v42, v[40:41], s[20:21]
	v_add_f32_e32 v128, v128, v129
	v_add_f32_e32 v130, v130, v131
	v_add_f32_e32 v149, v128, v130
	v_add_f32_dpp v142, v142, v142 quad_perm:[1,0,3,2] row_mask:0xf bank_mask:0xf bound_ctrl:1
	v_add_f32_dpp v143, v143, v143 quad_perm:[1,0,3,2] row_mask:0xf bank_mask:0xf bound_ctrl:1
	v_add_f32_dpp v144, v144, v144 quad_perm:[1,0,3,2] row_mask:0xf bank_mask:0xf bound_ctrl:1
	v_add_f32_dpp v145, v145, v145 quad_perm:[1,0,3,2] row_mask:0xf bank_mask:0xf bound_ctrl:1
	v_add_f32_dpp v146, v146, v146 quad_perm:[1,0,3,2] row_mask:0xf bank_mask:0xf bound_ctrl:1
	v_add_f32_dpp v147, v147, v147 quad_perm:[1,0,3,2] row_mask:0xf bank_mask:0xf bound_ctrl:1
	v_add_f32_dpp v148, v148, v148 quad_perm:[1,0,3,2] row_mask:0xf bank_mask:0xf bound_ctrl:1
	v_add_f32_dpp v149, v149, v149 quad_perm:[1,0,3,2] row_mask:0xf bank_mask:0xf bound_ctrl:1
	v_add_f32_dpp v142, v142, v142 quad_perm:[2,3,0,1] row_mask:0xf bank_mask:0xf bound_ctrl:1
	v_add_f32_dpp v143, v143, v143 quad_perm:[2,3,0,1] row_mask:0xf bank_mask:0xf bound_ctrl:1
	v_add_f32_dpp v144, v144, v144 quad_perm:[2,3,0,1] row_mask:0xf bank_mask:0xf bound_ctrl:1
	v_add_f32_dpp v145, v145, v145 quad_perm:[2,3,0,1] row_mask:0xf bank_mask:0xf bound_ctrl:1
	v_add_f32_dpp v146, v146, v146 quad_perm:[2,3,0,1] row_mask:0xf bank_mask:0xf bound_ctrl:1
	v_add_f32_dpp v147, v147, v147 quad_perm:[2,3,0,1] row_mask:0xf bank_mask:0xf bound_ctrl:1
	v_add_f32_dpp v148, v148, v148 quad_perm:[2,3,0,1] row_mask:0xf bank_mask:0xf bound_ctrl:1
	v_add_f32_dpp v149, v149, v149 quad_perm:[2,3,0,1] row_mask:0xf bank_mask:0xf bound_ctrl:1
	v_add_f32_dpp v142, v142, v142 row_half_mirror row_mask:0xf bank_mask:0xf bound_ctrl:1
	v_add_f32_dpp v143, v143, v143 row_half_mirror row_mask:0xf bank_mask:0xf bound_ctrl:1
	v_add_f32_dpp v144, v144, v144 row_half_mirror row_mask:0xf bank_mask:0xf bound_ctrl:1
	v_add_f32_dpp v145, v145, v145 row_half_mirror row_mask:0xf bank_mask:0xf bound_ctrl:1
	v_add_f32_dpp v146, v146, v146 row_half_mirror row_mask:0xf bank_mask:0xf bound_ctrl:1
	v_add_f32_dpp v147, v147, v147 row_half_mirror row_mask:0xf bank_mask:0xf bound_ctrl:1
	v_add_f32_dpp v148, v148, v148 row_half_mirror row_mask:0xf bank_mask:0xf bound_ctrl:1
	v_add_f32_dpp v149, v149, v149 row_half_mirror row_mask:0xf bank_mask:0xf bound_ctrl:1
	v_add_f32_dpp v142, v142, v142 row_mirror row_mask:0xf bank_mask:0xf bound_ctrl:1
	v_add_f32_dpp v143, v143, v143 row_mirror row_mask:0xf bank_mask:0xf bound_ctrl:1
	v_add_f32_dpp v144, v144, v144 row_mirror row_mask:0xf bank_mask:0xf bound_ctrl:1
	v_add_f32_dpp v145, v145, v145 row_mirror row_mask:0xf bank_mask:0xf bound_ctrl:1
	v_add_f32_dpp v146, v146, v146 row_mirror row_mask:0xf bank_mask:0xf bound_ctrl:1
	v_add_f32_dpp v147, v147, v147 row_mirror row_mask:0xf bank_mask:0xf bound_ctrl:1
	v_add_f32_dpp v148, v148, v148 row_mirror row_mask:0xf bank_mask:0xf bound_ctrl:1
	v_add_f32_dpp v149, v149, v149 row_mirror row_mask:0xf bank_mask:0xf bound_ctrl:1
	ds_bpermute_b32 v12, v176, v142
	ds_bpermute_b32 v16, v176, v143
	ds_bpermute_b32 v20, v176, v144
	ds_bpermute_b32 v24, v176, v145
	ds_bpermute_b32 v28, v176, v146
	ds_bpermute_b32 v32, v176, v147
	ds_bpermute_b32 v36, v176, v148
	ds_bpermute_b32 v40, v176, v149
	s_waitcnt lgkmcnt(0)
	v_add_f32_e32 v142, v142, v12
	v_add_f32_e32 v143, v143, v16
	v_add_f32_e32 v144, v144, v20
	v_add_f32_e32 v145, v145, v24
	v_add_f32_e32 v146, v146, v28
	v_add_f32_e32 v147, v147, v32
	v_add_f32_e32 v148, v148, v36
	v_add_f32_e32 v149, v149, v40
	v_add_u32_e32 v13, 0x0, v175
	v_add_u32_e32 v17, 0x40, v175
	v_add_u32_e32 v21, 0x80, v175
	v_add_u32_e32 v25, 0xc0, v175
	v_add_u32_e32 v29, 0x100, v175
	v_add_u32_e32 v33, 0x140, v175
	v_add_u32_e32 v37, 0x180, v175
	v_add_u32_e32 v41, 0x1c0, v175
	s_mov_b64 exec, s[0:1]
	global_atomic_add_f32 v13, v142, s[50:51]
	global_atomic_add_f32 v17, v143, s[50:51]
	global_atomic_add_f32 v21, v144, s[50:51]
	global_atomic_add_f32 v25, v145, s[50:51]
	global_atomic_add_f32 v29, v146, s[50:51]
	global_atomic_add_f32 v33, v147, s[50:51]
	global_atomic_add_f32 v37, v148, s[50:51]
	global_atomic_add_f32 v41, v149, s[50:51]
	s_mov_b64 exec, -1
	s_branch .LBB0_280
.Lcepi_last_b3:
	ds_read_b128 v[12:15], v171 offset:0
	v_mov_b32_e32 v134, v174
	global_load_dwordx4 v[100:103], v134, s[92:93]
	ds_read_b128 v[16:19], v171 offset:8448
	v_add_u32_e32 v135, 0x10000, v174
	global_load_dwordx4 v[104:107], v135, s[92:93]
	ds_read_b128 v[20:23], v171 offset:16896
	v_add_u32_e32 v136, 0x20000, v174
	global_load_dwordx4 v[108:111], v136, s[92:93]
	ds_read_b128 v[24:27], v171 offset:25344
	v_add_u32_e32 v137, 0x30000, v174
	global_load_dwordx4 v[112:115], v137, s[92:93]
	ds_read_b128 v[28:31], v171 offset:33792
	v_add_u32_e32 v138, 0x40000, v174
	global_load_dwordx4 v[116:119], v138, s[92:93]
	ds_read_b128 v[32:35], v171 offset:42240
	v_add_u32_e32 v139, 0x50000, v174
	global_load_dwordx4 v[120:123], v139, s[92:93]
	ds_read_b128 v[36:39], v171 offset:50688
	v_add_u32_e32 v140, 0x60000, v174
	global_load_dwordx4 v[124:127], v140, s[92:93]
	ds_read_b128 v[40:43], v171 offset:59136
	v_add_u32_e32 v141, 0x70000, v174
	global_load_dwordx4 v[128:131], v141, s[92:93]
	s_waitcnt vmcnt(7) lgkmcnt(7)
	v_pk_add_f32 v[100:101], v[100:101], v[12:13]
	v_pk_add_f32 v[102:103], v[102:103], v[14:15]
	global_store_dwordx4 v134, v[100:103], s[92:93]
	s_waitcnt vmcnt(7) lgkmcnt(6)
	v_pk_add_f32 v[104:105], v[104:105], v[16:17]
	v_pk_add_f32 v[106:107], v[106:107], v[18:19]
	global_store_dwordx4 v135, v[104:107], s[92:93]
	s_waitcnt vmcnt(7) lgkmcnt(5)
	v_pk_add_f32 v[108:109], v[108:109], v[20:21]
	v_pk_add_f32 v[110:111], v[110:111], v[22:23]
	global_store_dwordx4 v136, v[108:111], s[92:93]
	s_waitcnt vmcnt(7) lgkmcnt(4)
	v_pk_add_f32 v[112:113], v[112:113], v[24:25]
	v_pk_add_f32 v[114:115], v[114:115], v[26:27]
	global_store_dwordx4 v137, v[112:115], s[92:93]
	s_waitcnt vmcnt(7) lgkmcnt(3)
	v_pk_add_f32 v[116:117], v[116:117], v[28:29]
	v_pk_add_f32 v[118:119], v[118:119], v[30:31]
	global_store_dwordx4 v138, v[116:119], s[92:93]
	s_waitcnt vmcnt(7) lgkmcnt(2)
	v_pk_add_f32 v[120:121], v[120:121], v[32:33]
	v_pk_add_f32 v[122:123], v[122:123], v[34:35]
	global_store_dwordx4 v139, v[120:123], s[92:93]
	s_waitcnt vmcnt(7) lgkmcnt(1)
	v_pk_add_f32 v[124:125], v[124:125], v[36:37]
	v_pk_add_f32 v[126:127], v[126:127], v[38:39]
	global_store_dwordx4 v140, v[124:127], s[92:93]
	s_waitcnt vmcnt(7) lgkmcnt(0)
	v_pk_add_f32 v[128:129], v[128:129], v[40:41]
	v_pk_add_f32 v[130:131], v[130:131], v[42:43]
	global_store_dwordx4 v141, v[128:131], s[92:93]
	s_branch .LBB0_280

.LBB0_747:
	v_mov_b32_e32 v78, v133
	s_lshl_b32 s2, s2, 8
	v_ashrrev_i32_e32 v6, 6, v78
	v_bfe_u32 v7, v78, 3, 3
	v_lshl_or_b32 v8, v6, 5, v7
	v_add_u32_e32 v0, s2, v8
	s_waitcnt lgkmcnt(0)
	v_ashrrev_i32_e32 v1, 31, v0
	v_lshlrev_b64 v[2:3], 11, v[0:1]
	v_bfe_u32 v1, v78, 4, 2
	v_readlane_b32 s0, v215, 52
	v_xor_b32_e32 v1, v1, v78
	v_readlane_b32 s1, v215, 53
	v_lshlrev_b32_e32 v1, 4, v1
	v_and_b32_e32 v64, 0x70, v1
	v_lshl_add_u64 v[2:3], s[0:1], 0, v[2:3]
	v_or_b32_e32 v1, 8, v8
	v_lshl_add_u64 v[66:67], v[2:3], 0, v[64:65]
	v_add_u32_e32 v2, s2, v1
	v_lshrrev_b32_e32 v1, 1, v1
	v_xor_b32_e32 v1, v1, v78
	v_ashrrev_i32_e32 v3, 31, v2
	v_lshlrev_b32_e32 v1, 4, v1
	v_or_b32_e32 v0, 16, v0
	v_lshlrev_b64 v[2:3], 11, v[2:3]
	v_and_b32_e32 v4, 0x70, v1
	v_ashrrev_i32_e32 v1, 31, v0
	v_lshl_add_u64 v[2:3], s[0:1], 0, v[2:3]
	v_mov_b32_e32 v5, v65
	v_lshlrev_b64 v[0:1], 11, v[0:1]
	v_lshl_add_u64 v[68:69], v[2:3], 0, v[4:5]
	v_lshl_add_u64 v[0:1], s[0:1], 0, v[0:1]
	v_or_b32_e32 v2, 24, v8
	v_lshl_add_u64 v[70:71], v[0:1], 0, v[64:65]
	v_add_u32_e32 v0, s2, v2
	v_lshrrev_b32_e32 v2, 1, v2
	v_ashrrev_i32_e32 v1, 31, v0
	v_xor_b32_e32 v2, v2, v78
	v_lshlrev_b64 v[0:1], 11, v[0:1]
	v_lshlrev_b32_e32 v2, 4, v2
	v_lshl_add_u64 v[0:1], s[0:1], 0, v[0:1]
	v_and_b32_e32 v2, 0x70, v2
	v_mov_b32_e32 v3, v65
	v_lshl_add_u64 v[72:73], v[0:1], 0, v[2:3]
	v_lshl_or_b32 v2, v6, 4, v7
	v_add_u32_e32 v0, s20, v2
	v_lshlrev_b32_e32 v3, 12, v6
	v_ashrrev_i32_e32 v1, 31, v0
	v_add_u32_e32 v131, 0, v3
	v_lshlrev_b64 v[0:1], 11, v[0:1]
	s_waitcnt vmcnt(0)
	v_readfirstlane_b32 s40, v131
	v_add_u32_e32 v130, 0x400, v131
	v_lshl_add_u64 v[0:1], s[96:97], 0, v[0:1]
	v_or_b32_e32 v2, 8, v2
	s_waitcnt lgkmcnt(0)
	s_barrier
	s_mov_b32 m0, s40
	v_readfirstlane_b32 s41, v130
	v_add_u32_e32 v128, 0x800, v131
	v_lshlrev_b32_e32 v5, 11, v6
	v_and_b32_e32 v79, 1, v6
	v_lshl_add_u64 v[74:75], v[0:1], 0, v[64:65]
	v_add_u32_e32 v0, s20, v2
	v_lshrrev_b32_e32 v2, 1, v2
	global_load_lds_dwordx4 v[66:67], off
	s_mov_b32 m0, s41
	v_readfirstlane_b32 s42, v128
	v_add_u32_e32 v126, 0xc00, v131
	v_add_u32_e32 v6, 0, v5
	v_ashrrev_i32_e32 v1, 31, v0
	v_xor_b32_e32 v2, v2, v78
	global_load_lds_dwordx4 v[68:69], off
	s_mov_b32 m0, s42
	v_readfirstlane_b32 s43, v126
	v_add_u32_e32 v129, 0x8000, v6
	v_lshlrev_b64 v[0:1], 11, v[0:1]
	v_lshlrev_b32_e32 v2, 4, v2
	global_load_lds_dwordx4 v[70:71], off
	s_mov_b32 m0, s43
	v_readfirstlane_b32 s44, v129
	v_add_u32_e32 v127, 0x8400, v6
	v_lshl_add_u64 v[0:1], s[96:97], 0, v[0:1]
	v_and_b32_e32 v64, 0x70, v2
	global_load_lds_dwordx4 v[72:73], off
	s_mov_b32 m0, s44
	v_readfirstlane_b32 s45, v127
	v_add_u32_e32 v125, 0xc000, v131
	v_lshl_add_u64 v[76:77], v[0:1], 0, v[64:65]
	global_load_lds_dwordx4 v[74:75], off
	s_mov_b32 m0, s45
	s_mov_b64 s[0:1], 0x80
	v_readfirstlane_b32 s29, v125
	v_add_u32_e32 v120, 0xc400, v131
	global_load_lds_dwordx4 v[76:77], off
	v_lshl_add_u64 v[0:1], v[66:67], 0, s[0:1]
	s_mov_b32 m0, s29
	v_readfirstlane_b32 s33, v120
	v_add_u32_e32 v121, 0xc800, v131
	global_load_lds_dwordx4 v[0:1], off
	v_lshl_add_u64 v[0:1], v[68:69], 0, s[0:1]
	s_mov_b32 m0, s33
	v_readfirstlane_b32 s36, v121
	v_add_u32_e32 v122, 0xcc00, v131
	global_load_lds_dwordx4 v[0:1], off
	v_lshl_add_u64 v[0:1], v[70:71], 0, s[0:1]
	s_mov_b32 m0, s36
	v_readfirstlane_b32 s37, v122
	v_add_u32_e32 v123, s85, v5
	global_load_lds_dwordx4 v[0:1], off
	v_lshl_add_u64 v[0:1], v[72:73], 0, s[0:1]
	s_mov_b32 m0, s37
	v_readfirstlane_b32 s38, v123
	v_add_u32_e32 v124, 0x14400, v6
	global_load_lds_dwordx4 v[0:1], off
	v_lshl_add_u64 v[0:1], v[74:75], 0, s[0:1]
	s_mov_b32 m0, s38
	v_readfirstlane_b32 s39, v124
	global_load_lds_dwordx4 v[0:1], off
	v_lshl_add_u64 v[0:1], v[76:77], 0, s[0:1]
	s_mov_b32 m0, s39
	v_lshrrev_b32_e32 v2, 1, v78
	v_bfe_u32 v64, v78, 5, 1
	global_load_lds_dwordx4 v[0:1], off
	v_add_u32_e32 v119, s3, v3
	v_bitop3_b32 v0, v2, v64, 7 bitop3:0x6c
	s_waitcnt vmcnt(6)
	s_mov_b64 s[30:31], 0x100
	v_readfirstlane_b32 s0, v119
	v_add_u32_e32 v114, 0x400, v119
	v_lshlrev_b32_e32 v132, 4, v0
	s_waitcnt lgkmcnt(0)
	s_barrier
	v_lshl_add_u64 v[0:1], v[66:67], 0, s[30:31]
	s_mov_b32 m0, s0
	v_readfirstlane_b32 s1, v114
	v_add_u32_e32 v115, 0x800, v119
	global_load_lds_dwordx4 v[0:1], off
	v_lshl_add_u64 v[0:1], v[68:69], 0, s[30:31]
	s_mov_b32 m0, s1
	v_readfirstlane_b32 s21, v115
	v_add_u32_e32 v116, 0xc00, v119
	v_readlane_b32 s23, v212, 31
	v_and_b32_e32 v81, 31, v78
	global_load_lds_dwordx4 v[0:1], off
	v_lshl_add_u64 v[0:1], v[70:71], 0, s[30:31]
	s_mov_b32 m0, s21
	v_readfirstlane_b32 s22, v116
	v_add_u32_e32 v117, s23, v5
	v_add_u32_e32 v2, s3, v5
	v_lshlrev_b32_e32 v4, 7, v81
	global_load_lds_dwordx4 v[0:1], off
	v_lshl_add_u64 v[0:1], v[72:73], 0, s[30:31]
	s_mov_b32 m0, s22
	v_readfirstlane_b32 s23, v117
	v_add_u32_e32 v118, 0x8400, v2
	v_lshl_or_b32 v102, v79, 13, v4
	global_load_lds_dwordx4 v[0:1], off
	v_lshl_add_u64 v[0:1], v[74:75], 0, s[30:31]
	s_mov_b32 m0, s23
	v_readfirstlane_b32 s28, v118
	global_load_lds_dwordx4 v[0:1], off
	v_lshl_add_u64 v[0:1], v[76:77], 0, s[30:31]
	s_mov_b32 m0, s28
	v_add_u32_e32 v100, 0, v102
	global_load_lds_dwordx4 v[0:1], off
	v_add_u32_e32 v85, v100, v132
	v_ashrrev_i32_e32 v80, 7, v78
	ds_read_b128 v[0:3], v85 offset:32768
	ds_read_b128 v[86:89], v85 offset:36864
	v_lshl_or_b32 v134, v80, 13, v4
	v_add_u32_e32 v101, 0, v134
	v_add_u32_e32 v84, v101, v132
	ds_read_b128 v[4:7], v84
	v_bfe_u32 v103, v78, 1, 3
	s_waitcnt lgkmcnt(0)
	v_lshrrev_b32_e32 v182, 6, v133
	s_nop 0
	v_readfirstlane_b32 s32, v182
	v_mfma_f32_32x32x16_bf16 v[48:63], v[0:3], v[4:7], 0
	v_bitop3_b32 v8, v64, v103, 2 bitop3:0x36
	v_lshlrev_b32_e32 v135, 4, v8
	v_add_u32_e32 v83, v100, v135
	ds_read_b128 v[8:11], v83 offset:32768
	ds_read_b128 v[90:93], v83 offset:36864
	v_add_u32_e32 v82, v101, v135
	ds_read_b128 v[12:15], v82
	ds_read_b128 v[94:97], v82 offset:4096
	s_waitcnt vmcnt(12)
	v_mfma_f32_32x32x16_bf16 v[32:47], v[86:89], v[4:7], 0
	ds_read_b128 v[4:7], v84 offset:4096
	s_mov_b64 s[30:31], 0x180
	s_nop 0
	v_or_b32_e32 v143, 0x8000, v102
	v_or_b32_e32 v144, 0x9000, v102
	v_add_u32_e32 v145, s3, v134
	s_mov_b64 s[80:81], 0x200
	s_waitcnt lgkmcnt(0)
	v_mfma_f32_32x32x16_bf16 v[16:31], v[0:3], v[4:7], 0
	v_mfma_f32_32x32x16_bf16 v[48:63], v[8:11], v[12:15], v[48:63]
	v_mfma_f32_32x32x16_bf16 v[32:47], v[90:93], v[12:15], v[32:47]
	v_mfma_f32_32x32x16_bf16 v[16:31], v[8:11], v[94:97], v[16:31]
	v_mfma_f32_32x32x16_bf16 v[0:15], v[86:89], v[4:7], 0
	v_bitop3_b32 v86, v64, v103, 4 bitop3:0x36
	v_lshlrev_b32_e32 v138, 4, v86
	v_add_u32_e32 v87, v100, v138
	v_add_u32_e32 v86, v101, v138
	v_mfma_f32_32x32x16_bf16 v[0:15], v[90:93], v[94:97], v[0:15]
	ds_read_b128 v[88:91], v87 offset:32768
	ds_read_b128 v[92:95], v86
	ds_read_b128 v[96:99], v87 offset:36864
	s_waitcnt lgkmcnt(1)
	v_mfma_f32_32x32x16_bf16 v[48:63], v[88:91], v[92:95], v[48:63]
	s_waitcnt lgkmcnt(0)
	v_mfma_f32_32x32x16_bf16 v[32:47], v[96:99], v[92:95], v[32:47]
	ds_read_b128 v[92:95], v86 offset:4096
	s_waitcnt lgkmcnt(0)
	v_mfma_f32_32x32x16_bf16 v[16:31], v[88:91], v[92:95], v[16:31]
	v_bitop3_b32 v88, v64, v103, 6 bitop3:0x36
	v_lshlrev_b32_e32 v142, 4, v88
	v_add_u32_e32 v89, v100, v142
	v_add_u32_e32 v88, v101, v142
	v_mfma_f32_32x32x16_bf16 v[0:15], v[96:99], v[92:95], v[0:15]
	ds_read_b128 v[90:93], v89 offset:32768
	ds_read_b128 v[94:97], v88
	ds_read_b128 v[98:101], v89 offset:36864
	s_waitcnt lgkmcnt(1)
	v_mfma_f32_32x32x16_bf16 v[48:63], v[90:93], v[94:97], v[48:63]
	s_waitcnt lgkmcnt(0)
	v_mfma_f32_32x32x16_bf16 v[32:47], v[98:101], v[94:97], v[32:47]
	ds_read_b128 v[94:97], v88 offset:4096
	s_waitcnt vmcnt(6)
	s_waitcnt lgkmcnt(0)
	s_barrier
	s_waitcnt lgkmcnt(0)
	v_mfma_f32_32x32x16_bf16 v[16:31], v[90:93], v[94:97], v[16:31]
	v_lshl_add_u64 v[158:159], v[66:67], 0, s[30:31]
	s_nop 0
	v_lshl_add_u64 v[160:161], v[68:69], 0, s[30:31]
	s_nop 0
	s_nop 0
	s_nop 0
	v_lshl_add_u64 v[162:163], v[70:71], 0, s[30:31]
	s_nop 0
	v_mfma_f32_32x32x16_bf16 v[0:15], v[98:101], v[94:97], v[0:15]
	s_and_b32 m0, s32, 7
	s_lshl_b32 m0, m0, 12
	s_add_i32 m0, m0, 0x0
	s_nop 0
	global_load_lds_dwordx4 v[158:159], off
	s_nop 0
	v_lshl_add_u64 v[164:165], v[72:73], 0, s[30:31]
	s_nop 0
	s_nop 0
	s_nop 0
	v_lshl_add_u64 v[166:167], v[74:75], 0, s[30:31]
	s_nop 0
	s_nop 0
	s_nop 0
	v_lshl_add_u64 v[168:169], v[76:77], 0, s[30:31]
	s_nop 0
	s_add_i32 s30, 0, 0xc000
	s_nop 0
	v_add_u32_e32 v90, s30, v132
	v_add_u32_e32 v91, v90, v143
	v_add_u32_e32 v90, v90, v144
	ds_read_b128 v[92:95], v91
	ds_read_b128 v[96:99], v84 offset:49152
	ds_read_b128 v[100:103], v90
	ds_read_b128 v[150:153], v84 offset:53248
	s_waitcnt lgkmcnt(1)
	v_mfma_f32_32x32x16_bf16 v[48:63], v[92:95], v[96:99], v[48:63]
	s_nop 0
	v_mfma_f32_32x32x16_bf16 v[32:47], v[100:103], v[96:99], v[32:47]
	s_and_b32 m0, s32, 7
	s_lshl_b32 m0, m0, 12
	s_add_i32 m0, m0, 0x400
	s_nop 0
	global_load_lds_dwordx4 v[160:161], off
	s_waitcnt lgkmcnt(0)
	v_mfma_f32_32x32x16_bf16 v[16:31], v[92:95], v[150:153], v[16:31]
	v_add_u32_e32 v92, s30, v135
	v_add_u32_e32 v94, v92, v143
	v_add_u32_e32 v92, v92, v144
	v_add_u32_e32 v93, s30, v138
	v_add_u32_e32 v95, v93, v143
	v_add_u32_e32 v93, v93, v144
	v_mfma_f32_32x32x16_bf16 v[0:15], v[100:103], v[150:153], v[0:15]
	s_and_b32 m0, s32, 7
	s_lshl_b32 m0, m0, 12
	s_add_i32 m0, m0, 0x800
	s_nop 0
	global_load_lds_dwordx4 v[162:163], off
	ds_read_b128 v[96:99], v94
	ds_read_b128 v[100:103], v82 offset:49152
	ds_read_b128 v[104:107], v92
	ds_read_b128 v[154:157], v82 offset:53248
	s_waitcnt lgkmcnt(1)
	v_mfma_f32_32x32x16_bf16 v[48:63], v[96:99], v[100:103], v[48:63]
	v_mfma_f32_32x32x16_bf16 v[32:47], v[104:107], v[100:103], v[32:47]
	s_and_b32 m0, s32, 7
	s_lshl_b32 m0, m0, 12
	s_add_i32 m0, m0, 0xc00
	s_nop 0
	global_load_lds_dwordx4 v[164:165], off
	s_waitcnt lgkmcnt(0)
	v_mfma_f32_32x32x16_bf16 v[16:31], v[96:99], v[154:157], v[16:31]
	v_mfma_f32_32x32x16_bf16 v[0:15], v[104:107], v[154:157], v[0:15]
	s_and_b32 m0, s32, 7
	s_lshl_b32 m0, m0, 11
	s_add_i32 m0, m0, 0x8000
	s_nop 0
	global_load_lds_dwordx4 v[166:167], off
	ds_read_b128 v[96:99], v95
	ds_read_b128 v[100:103], v86 offset:49152
	ds_read_b128 v[104:107], v93
	ds_read_b128 v[150:153], v86 offset:53248
	s_waitcnt lgkmcnt(1)
	v_mfma_f32_32x32x16_bf16 v[48:63], v[96:99], v[100:103], v[48:63]
	v_mfma_f32_32x32x16_bf16 v[32:47], v[104:107], v[100:103], v[32:47]
	s_and_b32 m0, s32, 7
	s_lshl_b32 m0, m0, 11
	s_add_i32 m0, m0, 0x8400
	s_nop 0
	global_load_lds_dwordx4 v[168:169], off
	s_waitcnt lgkmcnt(0)
	v_mfma_f32_32x32x16_bf16 v[16:31], v[96:99], v[150:153], v[16:31]
	v_add_u32_e32 v96, s30, v142
	v_add_u32_e32 v97, v96, v143
	v_add_u32_e32 v96, v96, v144
	s_mov_b64 s[30:31], 0x200
	v_mfma_f32_32x32x16_bf16 v[0:15], v[104:107], v[150:153], v[0:15]
	ds_read_b128 v[98:101], v97
	ds_read_b128 v[102:105], v88 offset:49152
	ds_read_b128 v[106:109], v96
	ds_read_b128 v[154:157], v88 offset:53248
	s_waitcnt lgkmcnt(1)
	v_mfma_f32_32x32x16_bf16 v[48:63], v[98:101], v[102:105], v[48:63]
	v_mfma_f32_32x32x16_bf16 v[32:47], v[106:109], v[102:105], v[32:47]
	s_waitcnt vmcnt(6)
	s_waitcnt lgkmcnt(0)
	s_barrier
	s_waitcnt lgkmcnt(0)
	v_mfma_f32_32x32x16_bf16 v[16:31], v[98:101], v[154:157], v[16:31]
	v_lshl_add_u64 v[170:171], v[66:67], 0, s[30:31]
	s_nop 0
	v_lshl_add_u64 v[172:173], v[68:69], 0, s[30:31]
	s_nop 0
	v_add_u32_e32 v101, s3, v132
	s_nop 0
	v_lshl_add_u64 v[174:175], v[70:71], 0, s[30:31]
	s_nop 0
	v_mfma_f32_32x32x16_bf16 v[0:15], v[106:109], v[154:157], v[0:15]
	s_and_b32 m0, s32, 7
	s_lshl_b32 m0, m0, 12
	s_add_i32 m0, m0, 0xc000
	s_nop 0
	global_load_lds_dwordx4 v[170:171], off
	s_nop 0
	v_lshl_add_u64 v[176:177], v[72:73], 0, s[30:31]
	s_nop 0
	v_add_u32_e32 v100, v145, v132
	s_nop 0
	v_lshl_add_u64 v[178:179], v[74:75], 0, s[30:31]
	s_nop 0
	v_or_b32_e32 v132, 0x1000, v134
	s_nop 0
	v_lshl_add_u64 v[180:181], v[76:77], 0, s[30:31]
	s_nop 0
	s_mov_b64 s[30:31], 0x280
	s_nop 0
	v_add_u32_e32 v98, v101, v143
	v_add_u32_e32 v99, v101, v144
	ds_read_b128 v[110:113], v98
	ds_read_b128 v[106:109], v99
	ds_read_b128 v[102:105], v100
	v_add_u32_e32 v101, v101, v132
	ds_read_b128 v[150:153], v101
	s_waitcnt lgkmcnt(1)
	v_mfma_f32_32x32x16_bf16 v[48:63], v[110:113], v[102:105], v[48:63]
	s_nop 0
	v_mfma_f32_32x32x16_bf16 v[32:47], v[106:109], v[102:105], v[32:47]
	s_and_b32 m0, s32, 7
	s_lshl_b32 m0, m0, 12
	s_add_i32 m0, m0, 0xc400
	s_nop 0
	global_load_lds_dwordx4 v[172:173], off
	s_waitcnt lgkmcnt(0)
	v_mfma_f32_32x32x16_bf16 v[16:31], v[110:113], v[150:153], v[16:31]
	v_mfma_f32_32x32x16_bf16 v[0:15], v[106:109], v[150:153], v[0:15]
	s_and_b32 m0, s32, 7
	s_lshl_b32 m0, m0, 12
	s_add_i32 m0, m0, 0xc800
	s_nop 0
	global_load_lds_dwordx4 v[174:175], off
	v_add_u32_e32 v105, s3, v135
	v_add_u32_e32 v103, v105, v143
	v_add_u32_e32 v102, v105, v144
	ds_read_b128 v[106:109], v103
	v_add_u32_e32 v104, v145, v135
	ds_read_b128 v[134:137], v102
	ds_read_b128 v[110:113], v104
	v_add_u32_e32 v105, v105, v132
	ds_read_b128 v[154:157], v105
	s_waitcnt lgkmcnt(1)
	v_mfma_f32_32x32x16_bf16 v[48:63], v[106:109], v[110:113], v[48:63]
	v_mfma_f32_32x32x16_bf16 v[32:47], v[134:137], v[110:113], v[32:47]
	s_and_b32 m0, s32, 7
	s_lshl_b32 m0, m0, 12
	s_add_i32 m0, m0, 0xcc00
	s_nop 0
	global_load_lds_dwordx4 v[176:177], off
	s_waitcnt lgkmcnt(0)
	v_mfma_f32_32x32x16_bf16 v[16:31], v[106:109], v[154:157], v[16:31]
	v_add_u32_e32 v109, s3, v138
	v_add_u32_e32 v107, v109, v143
	v_add_u32_e32 v106, v109, v144
	v_add_u32_e32 v108, v145, v138
	ds_read_b128 v[138:141], v106
	v_add_u32_e32 v109, v109, v132
	v_mfma_f32_32x32x16_bf16 v[0:15], v[134:137], v[154:157], v[0:15]
	s_and_b32 m0, s32, 7
	s_lshl_b32 m0, m0, 11
	s_add_i32 m0, m0, 0x14000
	s_nop 0
	global_load_lds_dwordx4 v[178:179], off
	ds_read_b128 v[110:113], v107
	ds_read_b128 v[134:137], v108
	ds_read_b128 v[150:153], v109
	s_waitcnt lgkmcnt(1)
	v_mfma_f32_32x32x16_bf16 v[48:63], v[110:113], v[134:137], v[48:63]
	v_mfma_f32_32x32x16_bf16 v[32:47], v[138:141], v[134:137], v[32:47]
	s_and_b32 m0, s32, 7
	s_lshl_b32 m0, m0, 11
	s_add_i32 m0, m0, 0x14400
	s_nop 0
	global_load_lds_dwordx4 v[180:181], off
	s_waitcnt lgkmcnt(0)
	v_mfma_f32_32x32x16_bf16 v[16:31], v[110:113], v[150:153], v[16:31]
	v_add_u32_e32 v113, s3, v142
	v_add_u32_e32 v111, v113, v143
	v_add_u32_e32 v110, v113, v144
	v_add_u32_e32 v112, v145, v142
	ds_read_b128 v[142:145], v110
	v_add_u32_e32 v113, v113, v132
	v_mfma_f32_32x32x16_bf16 v[0:15], v[138:141], v[150:153], v[0:15]
	ds_read_b128 v[134:137], v111
	ds_read_b128 v[138:141], v112
	ds_read_b128 v[154:157], v113
	s_waitcnt lgkmcnt(1)
	v_mfma_f32_32x32x16_bf16 v[48:63], v[134:137], v[138:141], v[48:63]
	v_mfma_f32_32x32x16_bf16 v[32:47], v[142:145], v[138:141], v[32:47]
	s_waitcnt vmcnt(6)
	s_waitcnt lgkmcnt(0)
	s_barrier
	s_waitcnt lgkmcnt(0)
	v_mfma_f32_32x32x16_bf16 v[16:31], v[134:137], v[154:157], v[16:31]
	v_lshl_add_u64 v[158:159], v[66:67], 0, s[30:31]
	s_nop 0
	v_lshl_add_u64 v[160:161], v[68:69], 0, s[30:31]
	s_nop 0
	s_nop 0
	s_nop 0
	v_lshl_add_u64 v[162:163], v[70:71], 0, s[30:31]
	s_nop 0
	v_mfma_f32_32x32x16_bf16 v[0:15], v[142:145], v[154:157], v[0:15]
	s_and_b32 m0, s32, 7
	s_lshl_b32 m0, m0, 12
	s_add_i32 m0, m0, 0x18000
	s_nop 0
	global_load_lds_dwordx4 v[158:159], off
	s_nop 0
	v_lshl_add_u64 v[164:165], v[72:73], 0, s[30:31]
	s_nop 0
	s_nop 0
	s_nop 0
	v_lshl_add_u64 v[166:167], v[74:75], 0, s[30:31]
	s_nop 0
	s_nop 0
	s_nop 0
	v_lshl_add_u64 v[168:169], v[76:77], 0, s[30:31]
	s_nop 0
	s_mov_b64 s[30:31], 0x300
	s_nop 0
	ds_read_b128 v[134:137], v85 offset:32768
	ds_read_b128 v[138:141], v84
	ds_read_b128 v[142:145], v85 offset:36864
	ds_read_b128 v[150:153], v84 offset:4096
	s_waitcnt lgkmcnt(1)
	v_mfma_f32_32x32x16_bf16 v[48:63], v[134:137], v[138:141], v[48:63]
	s_nop 0
	v_readfirstlane_b32 s40, v119
	v_mfma_f32_32x32x16_bf16 v[32:47], v[142:145], v[138:141], v[32:47]
	s_and_b32 m0, s32, 7
	s_lshl_b32 m0, m0, 12
	s_add_i32 m0, m0, 0x18400
	s_nop 0
	global_load_lds_dwordx4 v[160:161], off
	s_waitcnt lgkmcnt(0)
	v_mfma_f32_32x32x16_bf16 v[16:31], v[134:137], v[150:153], v[16:31]
	v_mfma_f32_32x32x16_bf16 v[0:15], v[142:145], v[150:153], v[0:15]
	s_and_b32 m0, s32, 7
	s_lshl_b32 m0, m0, 12
	s_add_i32 m0, m0, 0x18800
	s_nop 0
	global_load_lds_dwordx4 v[162:163], off
	ds_read_b128 v[134:137], v83 offset:32768
	ds_read_b128 v[138:141], v82
	ds_read_b128 v[142:145], v83 offset:36864
	ds_read_b128 v[154:157], v82 offset:4096
	s_waitcnt lgkmcnt(1)
	v_mfma_f32_32x32x16_bf16 v[48:63], v[134:137], v[138:141], v[48:63]
	v_mfma_f32_32x32x16_bf16 v[32:47], v[142:145], v[138:141], v[32:47]
	s_and_b32 m0, s32, 7
	s_lshl_b32 m0, m0, 12
	s_add_i32 m0, m0, 0x18c00
	s_nop 0
	global_load_lds_dwordx4 v[164:165], off
	s_waitcnt lgkmcnt(0)
	v_mfma_f32_32x32x16_bf16 v[16:31], v[134:137], v[154:157], v[16:31]
	v_mfma_f32_32x32x16_bf16 v[0:15], v[142:145], v[154:157], v[0:15]
	s_and_b32 m0, s32, 7
	s_lshl_b32 m0, m0, 11
	s_add_i32 m0, m0, 0x20000
	s_nop 0
	global_load_lds_dwordx4 v[166:167], off
	ds_read_b128 v[134:137], v87 offset:32768
	ds_read_b128 v[138:141], v86
	ds_read_b128 v[142:145], v87 offset:36864
	ds_read_b128 v[150:153], v86 offset:4096
	s_waitcnt lgkmcnt(1)
	v_mfma_f32_32x32x16_bf16 v[48:63], v[134:137], v[138:141], v[48:63]
	v_mfma_f32_32x32x16_bf16 v[32:47], v[142:145], v[138:141], v[32:47]
	s_and_b32 m0, s32, 7
	s_lshl_b32 m0, m0, 11
	s_add_i32 m0, m0, 0x20400
	s_nop 0
	global_load_lds_dwordx4 v[168:169], off
	s_waitcnt lgkmcnt(0)
	v_mfma_f32_32x32x16_bf16 v[16:31], v[134:137], v[150:153], v[16:31]
	v_mfma_f32_32x32x16_bf16 v[0:15], v[142:145], v[150:153], v[0:15]
	ds_read_b128 v[134:137], v89 offset:32768
	ds_read_b128 v[138:141], v88
	ds_read_b128 v[142:145], v89 offset:36864
	ds_read_b128 v[154:157], v88 offset:4096
	s_waitcnt lgkmcnt(1)
	v_mfma_f32_32x32x16_bf16 v[48:63], v[134:137], v[138:141], v[48:63]
	v_mfma_f32_32x32x16_bf16 v[32:47], v[142:145], v[138:141], v[32:47]
	s_waitcnt vmcnt(6)
	s_waitcnt lgkmcnt(0)
	s_barrier
	s_waitcnt lgkmcnt(0)
	v_mfma_f32_32x32x16_bf16 v[16:31], v[134:137], v[154:157], v[16:31]
	v_lshl_add_u64 v[170:171], v[66:67], 0, s[30:31]
	s_nop 0
	v_lshl_add_u64 v[172:173], v[68:69], 0, s[30:31]
	s_nop 0
	v_readfirstlane_b32 s41, v114
	s_nop 0
	v_lshl_add_u64 v[174:175], v[70:71], 0, s[30:31]
	s_nop 0
	v_mfma_f32_32x32x16_bf16 v[0:15], v[142:145], v[154:157], v[0:15]
	s_and_b32 m0, s32, 7
	s_lshl_b32 m0, m0, 12
	s_add_i32 m0, m0, 0x0
	s_nop 0
	global_load_lds_dwordx4 v[170:171], off
	s_nop 0
	v_lshl_add_u64 v[176:177], v[72:73], 0, s[30:31]
	s_nop 0
	v_readfirstlane_b32 s42, v115
	s_nop 0
	v_lshl_add_u64 v[178:179], v[74:75], 0, s[30:31]
	s_nop 0
	v_readfirstlane_b32 s43, v116
	s_nop 0
	v_lshl_add_u64 v[180:181], v[76:77], 0, s[30:31]
	s_nop 0
	s_mov_b64 s[30:31], 0x380
	s_nop 0
	ds_read_b128 v[134:137], v91
	ds_read_b128 v[138:141], v84 offset:49152
	ds_read_b128 v[142:145], v90
	ds_read_b128 v[150:153], v84 offset:53248
	s_waitcnt lgkmcnt(1)
	v_mfma_f32_32x32x16_bf16 v[48:63], v[134:137], v[138:141], v[48:63]
	s_nop 0
	v_readfirstlane_b32 s29, v125
	v_readfirstlane_b32 s44, v117
	v_readfirstlane_b32 s45, v118
	v_mfma_f32_32x32x16_bf16 v[32:47], v[142:145], v[138:141], v[32:47]
	s_and_b32 m0, s32, 7
	s_lshl_b32 m0, m0, 12
	s_add_i32 m0, m0, 0x400
	s_nop 0
	global_load_lds_dwordx4 v[172:173], off
	s_waitcnt lgkmcnt(0)
	v_mfma_f32_32x32x16_bf16 v[16:31], v[134:137], v[150:153], v[16:31]
	v_mfma_f32_32x32x16_bf16 v[0:15], v[142:145], v[150:153], v[0:15]
	s_and_b32 m0, s32, 7
	s_lshl_b32 m0, m0, 12
	s_add_i32 m0, m0, 0x800
	s_nop 0
	global_load_lds_dwordx4 v[174:175], off
	ds_read_b128 v[134:137], v94
	ds_read_b128 v[138:141], v82 offset:49152
	ds_read_b128 v[142:145], v92
	ds_read_b128 v[154:157], v82 offset:53248
	s_waitcnt lgkmcnt(1)
	v_mfma_f32_32x32x16_bf16 v[48:63], v[134:137], v[138:141], v[48:63]
	v_mfma_f32_32x32x16_bf16 v[32:47], v[142:145], v[138:141], v[32:47]
	s_and_b32 m0, s32, 7
	s_lshl_b32 m0, m0, 12
	s_add_i32 m0, m0, 0xc00
	s_nop 0
	global_load_lds_dwordx4 v[176:177], off
	s_waitcnt lgkmcnt(0)
	v_mfma_f32_32x32x16_bf16 v[16:31], v[134:137], v[154:157], v[16:31]
	v_mfma_f32_32x32x16_bf16 v[0:15], v[142:145], v[154:157], v[0:15]
	s_and_b32 m0, s32, 7
	s_lshl_b32 m0, m0, 11
	s_add_i32 m0, m0, 0x8000
	s_nop 0
	global_load_lds_dwordx4 v[178:179], off
	ds_read_b128 v[134:137], v95
	ds_read_b128 v[138:141], v86 offset:49152
	ds_read_b128 v[142:145], v93
	ds_read_b128 v[150:153], v86 offset:53248
	s_waitcnt lgkmcnt(1)
	v_mfma_f32_32x32x16_bf16 v[48:63], v[134:137], v[138:141], v[48:63]
	v_mfma_f32_32x32x16_bf16 v[32:47], v[142:145], v[138:141], v[32:47]
	s_and_b32 m0, s32, 7
	s_lshl_b32 m0, m0, 11
	s_add_i32 m0, m0, 0x8400
	s_nop 0
	global_load_lds_dwordx4 v[180:181], off
	s_waitcnt lgkmcnt(0)
	v_mfma_f32_32x32x16_bf16 v[16:31], v[134:137], v[150:153], v[16:31]
	v_mfma_f32_32x32x16_bf16 v[0:15], v[142:145], v[150:153], v[0:15]
	ds_read_b128 v[134:137], v97
	ds_read_b128 v[138:141], v88 offset:49152
	ds_read_b128 v[142:145], v96
	ds_read_b128 v[154:157], v88 offset:53248
	s_waitcnt lgkmcnt(1)
	v_mfma_f32_32x32x16_bf16 v[48:63], v[134:137], v[138:141], v[48:63]
	v_mfma_f32_32x32x16_bf16 v[32:47], v[142:145], v[138:141], v[32:47]
	s_waitcnt vmcnt(6)
	s_waitcnt lgkmcnt(0)
	s_barrier
	s_waitcnt lgkmcnt(0)
	v_mfma_f32_32x32x16_bf16 v[16:31], v[134:137], v[154:157], v[16:31]
	v_lshl_add_u64 v[158:159], v[66:67], 0, s[30:31]
	s_nop 0
	v_lshl_add_u64 v[160:161], v[68:69], 0, s[30:31]
	s_nop 0
	v_readfirstlane_b32 s33, v120
	s_nop 0
	v_lshl_add_u64 v[162:163], v[70:71], 0, s[30:31]
	s_nop 0
	v_mfma_f32_32x32x16_bf16 v[0:15], v[142:145], v[154:157], v[0:15]
	s_and_b32 m0, s32, 7
	s_lshl_b32 m0, m0, 12
	s_add_i32 m0, m0, 0xc000
	s_nop 0
	global_load_lds_dwordx4 v[158:159], off
	s_nop 0
	v_lshl_add_u64 v[164:165], v[72:73], 0, s[30:31]
	s_nop 0
	v_readfirstlane_b32 s36, v121
	s_nop 0
	v_lshl_add_u64 v[166:167], v[74:75], 0, s[30:31]
	s_nop 0
	v_readfirstlane_b32 s37, v122
	s_nop 0
	v_lshl_add_u64 v[168:169], v[76:77], 0, s[30:31]
	s_nop 0
	s_mov_b64 s[30:31], 0x400
	s_nop 0
	ds_read_b128 v[134:137], v98
	ds_read_b128 v[138:141], v100
	ds_read_b128 v[142:145], v99
	ds_read_b128 v[150:153], v101
	s_waitcnt lgkmcnt(1)
	v_mfma_f32_32x32x16_bf16 v[48:63], v[134:137], v[138:141], v[48:63]
	s_nop 0
	v_readfirstlane_b32 s0, v131
	v_readfirstlane_b32 s38, v123
	v_readfirstlane_b32 s39, v124
	v_mfma_f32_32x32x16_bf16 v[32:47], v[142:145], v[138:141], v[32:47]
	s_and_b32 m0, s32, 7
	s_lshl_b32 m0, m0, 12
	s_add_i32 m0, m0, 0xc400
	s_nop 0
	global_load_lds_dwordx4 v[160:161], off
	s_waitcnt lgkmcnt(0)
	v_mfma_f32_32x32x16_bf16 v[16:31], v[134:137], v[150:153], v[16:31]
	v_mfma_f32_32x32x16_bf16 v[0:15], v[142:145], v[150:153], v[0:15]
	s_and_b32 m0, s32, 7
	s_lshl_b32 m0, m0, 12
	s_add_i32 m0, m0, 0xc800
	s_nop 0
	global_load_lds_dwordx4 v[162:163], off
	ds_read_b128 v[134:137], v103
	ds_read_b128 v[138:141], v104
	ds_read_b128 v[142:145], v102
	ds_read_b128 v[154:157], v105
	s_waitcnt lgkmcnt(1)
	v_mfma_f32_32x32x16_bf16 v[48:63], v[134:137], v[138:141], v[48:63]
	v_mfma_f32_32x32x16_bf16 v[32:47], v[142:145], v[138:141], v[32:47]
	s_and_b32 m0, s32, 7
	s_lshl_b32 m0, m0, 12
	s_add_i32 m0, m0, 0xcc00
	s_nop 0
	global_load_lds_dwordx4 v[164:165], off
	s_waitcnt lgkmcnt(0)
	v_mfma_f32_32x32x16_bf16 v[16:31], v[134:137], v[154:157], v[16:31]
	v_mfma_f32_32x32x16_bf16 v[0:15], v[142:145], v[154:157], v[0:15]
	s_and_b32 m0, s32, 7
	s_lshl_b32 m0, m0, 11
	s_add_i32 m0, m0, 0x14000
	s_nop 0
	global_load_lds_dwordx4 v[166:167], off
	ds_read_b128 v[134:137], v107
	ds_read_b128 v[138:141], v108
	ds_read_b128 v[142:145], v106
	ds_read_b128 v[150:153], v109
	s_waitcnt lgkmcnt(1)
	v_mfma_f32_32x32x16_bf16 v[48:63], v[134:137], v[138:141], v[48:63]
	v_mfma_f32_32x32x16_bf16 v[32:47], v[142:145], v[138:141], v[32:47]
	s_and_b32 m0, s32, 7
	s_lshl_b32 m0, m0, 11
	s_add_i32 m0, m0, 0x14400
	s_nop 0
	global_load_lds_dwordx4 v[168:169], off
	s_waitcnt lgkmcnt(0)
	v_mfma_f32_32x32x16_bf16 v[16:31], v[134:137], v[150:153], v[16:31]
	v_mfma_f32_32x32x16_bf16 v[0:15], v[142:145], v[150:153], v[0:15]
	ds_read_b128 v[134:137], v111
	ds_read_b128 v[138:141], v112
	ds_read_b128 v[142:145], v110
	ds_read_b128 v[154:157], v113
	s_waitcnt lgkmcnt(1)
	v_mfma_f32_32x32x16_bf16 v[48:63], v[134:137], v[138:141], v[48:63]
	v_mfma_f32_32x32x16_bf16 v[32:47], v[142:145], v[138:141], v[32:47]
	s_waitcnt vmcnt(6)
	s_waitcnt lgkmcnt(0)
	s_barrier
	s_waitcnt lgkmcnt(0)
	v_mfma_f32_32x32x16_bf16 v[16:31], v[134:137], v[154:157], v[16:31]
	v_lshl_add_u64 v[170:171], v[66:67], 0, s[30:31]
	s_nop 0
	v_lshl_add_u64 v[172:173], v[68:69], 0, s[30:31]
	s_nop 0
	v_readfirstlane_b32 s1, v130
	s_nop 0
	v_lshl_add_u64 v[174:175], v[70:71], 0, s[30:31]
	s_nop 0
	v_mfma_f32_32x32x16_bf16 v[0:15], v[142:145], v[154:157], v[0:15]
	s_and_b32 m0, s32, 7
	s_lshl_b32 m0, m0, 12
	s_add_i32 m0, m0, 0x18000
	s_nop 0
	global_load_lds_dwordx4 v[170:171], off
	s_nop 0
	v_lshl_add_u64 v[176:177], v[72:73], 0, s[30:31]
	s_nop 0
	v_readfirstlane_b32 s21, v128
	s_nop 0
	v_lshl_add_u64 v[178:179], v[74:75], 0, s[30:31]
	s_nop 0
	v_readfirstlane_b32 s22, v126
	s_nop 0
	v_lshl_add_u64 v[180:181], v[76:77], 0, s[30:31]
	s_nop 0
	s_mov_b64 s[30:31], 0x480
	s_nop 0
	ds_read_b128 v[134:137], v85 offset:32768
	ds_read_b128 v[138:141], v84
	ds_read_b128 v[142:145], v85 offset:36864
	ds_read_b128 v[150:153], v84 offset:4096
	s_waitcnt lgkmcnt(1)
	v_mfma_f32_32x32x16_bf16 v[48:63], v[134:137], v[138:141], v[48:63]
	s_nop 0
	v_lshl_add_u64 v[160:161], v[68:69], 0, s[30:31]
	v_readfirstlane_b32 s23, v129
	v_lshl_add_u64 v[166:167], v[74:75], 0, s[30:31]
	v_readfirstlane_b32 s28, v127
	v_lshl_add_u64 v[168:169], v[76:77], 0, s[30:31]
	v_mfma_f32_32x32x16_bf16 v[32:47], v[142:145], v[138:141], v[32:47]
	s_and_b32 m0, s32, 7
	s_lshl_b32 m0, m0, 12
	s_add_i32 m0, m0, 0x18400
	s_nop 0
	global_load_lds_dwordx4 v[172:173], off
	s_waitcnt lgkmcnt(0)
	v_mfma_f32_32x32x16_bf16 v[16:31], v[134:137], v[150:153], v[16:31]
	v_mfma_f32_32x32x16_bf16 v[0:15], v[142:145], v[150:153], v[0:15]
	s_and_b32 m0, s32, 7
	s_lshl_b32 m0, m0, 12
	s_add_i32 m0, m0, 0x18800
	s_nop 0
	global_load_lds_dwordx4 v[174:175], off
	ds_read_b128 v[134:137], v83 offset:32768
	ds_read_b128 v[138:141], v82
	ds_read_b128 v[142:145], v83 offset:36864
	ds_read_b128 v[154:157], v82 offset:4096
	s_waitcnt lgkmcnt(1)
	v_mfma_f32_32x32x16_bf16 v[48:63], v[134:137], v[138:141], v[48:63]
	v_mfma_f32_32x32x16_bf16 v[32:47], v[142:145], v[138:141], v[32:47]
	s_and_b32 m0, s32, 7
	s_lshl_b32 m0, m0, 12
	s_add_i32 m0, m0, 0x18c00
	s_nop 0
	global_load_lds_dwordx4 v[176:177], off
	s_waitcnt lgkmcnt(0)
	v_mfma_f32_32x32x16_bf16 v[16:31], v[134:137], v[154:157], v[16:31]
	v_mfma_f32_32x32x16_bf16 v[0:15], v[142:145], v[154:157], v[0:15]
	s_and_b32 m0, s32, 7
	s_lshl_b32 m0, m0, 11
	s_add_i32 m0, m0, 0x20000
	s_nop 0
	global_load_lds_dwordx4 v[178:179], off
	ds_read_b128 v[134:137], v87 offset:32768
	ds_read_b128 v[138:141], v86
	ds_read_b128 v[142:145], v87 offset:36864
	ds_read_b128 v[150:153], v86 offset:4096
	s_waitcnt lgkmcnt(1)
	v_mfma_f32_32x32x16_bf16 v[48:63], v[134:137], v[138:141], v[48:63]
	v_mfma_f32_32x32x16_bf16 v[32:47], v[142:145], v[138:141], v[32:47]
	s_and_b32 m0, s32, 7
	s_lshl_b32 m0, m0, 11
	s_add_i32 m0, m0, 0x20400
	s_nop 0
	global_load_lds_dwordx4 v[180:181], off
	s_waitcnt lgkmcnt(0)
	v_mfma_f32_32x32x16_bf16 v[16:31], v[134:137], v[150:153], v[16:31]
	v_mfma_f32_32x32x16_bf16 v[0:15], v[142:145], v[150:153], v[0:15]
	ds_read_b128 v[134:137], v89 offset:32768
	ds_read_b128 v[138:141], v88
	ds_read_b128 v[142:145], v89 offset:36864
	ds_read_b128 v[154:157], v88 offset:4096
	s_waitcnt lgkmcnt(1)
	v_mfma_f32_32x32x16_bf16 v[48:63], v[134:137], v[138:141], v[48:63]
	v_mfma_f32_32x32x16_bf16 v[32:47], v[142:145], v[138:141], v[32:47]
	s_waitcnt vmcnt(6)
	s_waitcnt lgkmcnt(0)
	s_barrier
	s_waitcnt lgkmcnt(0)
	v_mfma_f32_32x32x16_bf16 v[16:31], v[134:137], v[154:157], v[16:31]
	v_lshl_add_u64 v[158:159], v[66:67], 0, s[30:31]
	s_nop 0
	s_nop 0
	s_nop 0
	s_nop 0
	v_lshl_add_u64 v[162:163], v[70:71], 0, s[30:31]
	s_nop 0
	v_mfma_f32_32x32x16_bf16 v[0:15], v[142:145], v[154:157], v[0:15]
	s_and_b32 m0, s32, 7
	s_lshl_b32 m0, m0, 12
	s_add_i32 m0, m0, 0x0
	s_nop 0
	global_load_lds_dwordx4 v[158:159], off
	s_nop 0
	v_lshl_add_u64 v[164:165], v[72:73], 0, s[30:31]
	s_nop 0
	s_mov_b64 s[30:31], 0x500
	s_nop 0
	s_nop 0
	v_lshl_add_u64 v[174:175], v[70:71], 0, s[30:31]
	s_nop 0
	s_nop 0
	s_nop 0
	s_nop 0
	ds_read_b128 v[126:129], v91
	ds_read_b128 v[134:137], v84 offset:49152
	ds_read_b128 v[138:141], v90
	ds_read_b128 v[150:153], v84 offset:53248
	s_waitcnt lgkmcnt(1)
	v_mfma_f32_32x32x16_bf16 v[48:63], v[126:129], v[134:137], v[48:63]
	s_nop 0
	v_mfma_f32_32x32x16_bf16 v[32:47], v[138:141], v[134:137], v[32:47]
	s_and_b32 m0, s32, 7
	s_lshl_b32 m0, m0, 12
	s_add_i32 m0, m0, 0x400
	s_nop 0
	global_load_lds_dwordx4 v[160:161], off
	s_waitcnt lgkmcnt(0)
	v_mfma_f32_32x32x16_bf16 v[16:31], v[126:129], v[150:153], v[16:31]
	v_mfma_f32_32x32x16_bf16 v[0:15], v[138:141], v[150:153], v[0:15]
	s_and_b32 m0, s32, 7
	s_lshl_b32 m0, m0, 12
	s_add_i32 m0, m0, 0x800
	s_nop 0
	global_load_lds_dwordx4 v[162:163], off
	ds_read_b128 v[126:129], v94
	ds_read_b128 v[134:137], v82 offset:49152
	ds_read_b128 v[138:141], v92
	ds_read_b128 v[154:157], v82 offset:53248
	s_waitcnt lgkmcnt(1)
	v_mfma_f32_32x32x16_bf16 v[48:63], v[126:129], v[134:137], v[48:63]
	v_mfma_f32_32x32x16_bf16 v[32:47], v[138:141], v[134:137], v[32:47]
	s_and_b32 m0, s32, 7
	s_lshl_b32 m0, m0, 12
	s_add_i32 m0, m0, 0xc00
	s_nop 0
	global_load_lds_dwordx4 v[164:165], off
	s_waitcnt lgkmcnt(0)
	v_mfma_f32_32x32x16_bf16 v[16:31], v[126:129], v[154:157], v[16:31]
	v_mfma_f32_32x32x16_bf16 v[0:15], v[138:141], v[154:157], v[0:15]
	s_and_b32 m0, s32, 7
	s_lshl_b32 m0, m0, 11
	s_add_i32 m0, m0, 0x8000
	s_nop 0
	global_load_lds_dwordx4 v[166:167], off
	ds_read_b128 v[126:129], v95
	ds_read_b128 v[134:137], v86 offset:49152
	ds_read_b128 v[138:141], v93
	ds_read_b128 v[150:153], v86 offset:53248
	s_waitcnt lgkmcnt(1)
	v_mfma_f32_32x32x16_bf16 v[48:63], v[126:129], v[134:137], v[48:63]
	v_mfma_f32_32x32x16_bf16 v[32:47], v[138:141], v[134:137], v[32:47]
	s_and_b32 m0, s32, 7
	s_lshl_b32 m0, m0, 11
	s_add_i32 m0, m0, 0x8400
	s_nop 0
	global_load_lds_dwordx4 v[168:169], off
	s_waitcnt lgkmcnt(0)
	v_mfma_f32_32x32x16_bf16 v[16:31], v[126:129], v[150:153], v[16:31]
	v_mfma_f32_32x32x16_bf16 v[0:15], v[138:141], v[150:153], v[0:15]
	ds_read_b128 v[126:129], v97
	ds_read_b128 v[134:137], v88 offset:49152
	ds_read_b128 v[138:141], v96
	ds_read_b128 v[154:157], v88 offset:53248
	s_waitcnt lgkmcnt(1)
	v_mfma_f32_32x32x16_bf16 v[48:63], v[126:129], v[134:137], v[48:63]
	v_mfma_f32_32x32x16_bf16 v[32:47], v[138:141], v[134:137], v[32:47]
	s_waitcnt vmcnt(6)
	s_waitcnt lgkmcnt(0)
	s_barrier
	s_waitcnt lgkmcnt(0)
	v_mfma_f32_32x32x16_bf16 v[16:31], v[126:129], v[154:157], v[16:31]
	v_lshl_add_u64 v[170:171], v[66:67], 0, s[30:31]
	s_nop 0
	v_lshl_add_u64 v[172:173], v[68:69], 0, s[30:31]
	s_nop 0
	s_nop 0
	s_nop 0
	s_nop 0
	v_mfma_f32_32x32x16_bf16 v[0:15], v[138:141], v[154:157], v[0:15]
	s_and_b32 m0, s32, 7
	s_lshl_b32 m0, m0, 12
	s_add_i32 m0, m0, 0xc000
	s_nop 0
	global_load_lds_dwordx4 v[170:171], off
	s_nop 0
	v_lshl_add_u64 v[176:177], v[72:73], 0, s[30:31]
	s_nop 0
	s_nop 0
	s_nop 0
	v_lshl_add_u64 v[178:179], v[74:75], 0, s[30:31]
	s_nop 0
	s_nop 0
	s_nop 0
	v_lshl_add_u64 v[180:181], v[76:77], 0, s[30:31]
	s_nop 0
	s_mov_b64 s[30:31], 0x580
	s_nop 0
	ds_read_b128 v[120:123], v98
	ds_read_b128 v[124:127], v100
	ds_read_b128 v[128:131], v99
	ds_read_b128 v[150:153], v101
	s_waitcnt lgkmcnt(1)
	v_mfma_f32_32x32x16_bf16 v[48:63], v[120:123], v[124:127], v[48:63]
	s_nop 0
	v_lshl_add_u64 v[162:163], v[70:71], 0, s[30:31]
	v_mfma_f32_32x32x16_bf16 v[32:47], v[128:131], v[124:127], v[32:47]
	s_and_b32 m0, s32, 7
	s_lshl_b32 m0, m0, 12
	s_add_i32 m0, m0, 0xc400
	s_nop 0
	global_load_lds_dwordx4 v[172:173], off
	s_waitcnt lgkmcnt(0)
	v_mfma_f32_32x32x16_bf16 v[16:31], v[120:123], v[150:153], v[16:31]
	v_mfma_f32_32x32x16_bf16 v[0:15], v[128:131], v[150:153], v[0:15]
	s_and_b32 m0, s32, 7
	s_lshl_b32 m0, m0, 12
	s_add_i32 m0, m0, 0xc800
	s_nop 0
	global_load_lds_dwordx4 v[174:175], off
	ds_read_b128 v[120:123], v103
	ds_read_b128 v[124:127], v104
	ds_read_b128 v[128:131], v102
	ds_read_b128 v[154:157], v105
	s_waitcnt lgkmcnt(1)
	v_mfma_f32_32x32x16_bf16 v[48:63], v[120:123], v[124:127], v[48:63]
	v_mfma_f32_32x32x16_bf16 v[32:47], v[128:131], v[124:127], v[32:47]
	s_and_b32 m0, s32, 7
	s_lshl_b32 m0, m0, 12
	s_add_i32 m0, m0, 0xcc00
	s_nop 0
	global_load_lds_dwordx4 v[176:177], off
	s_waitcnt lgkmcnt(0)
	v_mfma_f32_32x32x16_bf16 v[16:31], v[120:123], v[154:157], v[16:31]
	v_mfma_f32_32x32x16_bf16 v[0:15], v[128:131], v[154:157], v[0:15]
	s_and_b32 m0, s32, 7
	s_lshl_b32 m0, m0, 11
	s_add_i32 m0, m0, 0x14000
	s_nop 0
	global_load_lds_dwordx4 v[178:179], off
	ds_read_b128 v[120:123], v107
	ds_read_b128 v[124:127], v108
	ds_read_b128 v[128:131], v106
	ds_read_b128 v[150:153], v109
	s_waitcnt lgkmcnt(1)
	v_mfma_f32_32x32x16_bf16 v[48:63], v[120:123], v[124:127], v[48:63]
	v_mfma_f32_32x32x16_bf16 v[32:47], v[128:131], v[124:127], v[32:47]
	s_and_b32 m0, s32, 7
	s_lshl_b32 m0, m0, 11
	s_add_i32 m0, m0, 0x14400
	s_nop 0
	global_load_lds_dwordx4 v[180:181], off
	s_waitcnt lgkmcnt(0)
	v_mfma_f32_32x32x16_bf16 v[16:31], v[120:123], v[150:153], v[16:31]
	v_mfma_f32_32x32x16_bf16 v[0:15], v[128:131], v[150:153], v[0:15]
	ds_read_b128 v[120:123], v111
	ds_read_b128 v[124:127], v112
	ds_read_b128 v[128:131], v110
	ds_read_b128 v[154:157], v113
	s_waitcnt lgkmcnt(1)
	v_mfma_f32_32x32x16_bf16 v[48:63], v[120:123], v[124:127], v[48:63]
	v_mfma_f32_32x32x16_bf16 v[32:47], v[128:131], v[124:127], v[32:47]
	s_waitcnt vmcnt(6)
	s_waitcnt lgkmcnt(0)
	s_barrier
	s_waitcnt lgkmcnt(0)
	v_mfma_f32_32x32x16_bf16 v[16:31], v[120:123], v[154:157], v[16:31]
	v_lshl_add_u64 v[158:159], v[66:67], 0, s[30:31]
	s_nop 0
	v_lshl_add_u64 v[160:161], v[68:69], 0, s[30:31]
	s_nop 0
	s_nop 0
	s_nop 0
	s_nop 0
	v_mfma_f32_32x32x16_bf16 v[0:15], v[128:131], v[154:157], v[0:15]
	s_and_b32 m0, s32, 7
	s_lshl_b32 m0, m0, 12
	s_add_i32 m0, m0, 0x18000
	s_nop 0
	global_load_lds_dwordx4 v[158:159], off
	s_nop 0
	v_lshl_add_u64 v[164:165], v[72:73], 0, s[30:31]
	s_nop 0
	s_nop 0
	s_nop 0
	v_lshl_add_u64 v[166:167], v[74:75], 0, s[30:31]
	s_nop 0
	s_nop 0
	s_nop 0
	v_lshl_add_u64 v[168:169], v[76:77], 0, s[30:31]
	s_nop 0
	s_mov_b64 s[30:31], 0x600
	s_nop 0
	ds_read_b128 v[114:117], v85 offset:32768
	ds_read_b128 v[118:121], v84
	ds_read_b128 v[122:125], v85 offset:36864
	ds_read_b128 v[150:153], v84 offset:4096
	s_waitcnt lgkmcnt(1)
	v_mfma_f32_32x32x16_bf16 v[48:63], v[114:117], v[118:121], v[48:63]
	s_nop 0
	v_mfma_f32_32x32x16_bf16 v[32:47], v[122:125], v[118:121], v[32:47]
	s_and_b32 m0, s32, 7
	s_lshl_b32 m0, m0, 12
	s_add_i32 m0, m0, 0x18400
	s_nop 0
	global_load_lds_dwordx4 v[160:161], off
	s_waitcnt lgkmcnt(0)
	v_mfma_f32_32x32x16_bf16 v[16:31], v[114:117], v[150:153], v[16:31]
	v_mfma_f32_32x32x16_bf16 v[0:15], v[122:125], v[150:153], v[0:15]
	s_and_b32 m0, s32, 7
	s_lshl_b32 m0, m0, 12
	s_add_i32 m0, m0, 0x18800
	s_nop 0
	global_load_lds_dwordx4 v[162:163], off
	ds_read_b128 v[114:117], v83 offset:32768
	ds_read_b128 v[118:121], v82
	ds_read_b128 v[122:125], v83 offset:36864
	ds_read_b128 v[154:157], v82 offset:4096
	s_waitcnt lgkmcnt(1)
	v_mfma_f32_32x32x16_bf16 v[48:63], v[114:117], v[118:121], v[48:63]
	v_mfma_f32_32x32x16_bf16 v[32:47], v[122:125], v[118:121], v[32:47]
	s_and_b32 m0, s32, 7
	s_lshl_b32 m0, m0, 12
	s_add_i32 m0, m0, 0x18c00
	s_nop 0
	global_load_lds_dwordx4 v[164:165], off
	s_waitcnt lgkmcnt(0)
	v_mfma_f32_32x32x16_bf16 v[16:31], v[114:117], v[154:157], v[16:31]
	v_mfma_f32_32x32x16_bf16 v[0:15], v[122:125], v[154:157], v[0:15]
	s_and_b32 m0, s32, 7
	s_lshl_b32 m0, m0, 11
	s_add_i32 m0, m0, 0x20000
	s_nop 0
	global_load_lds_dwordx4 v[166:167], off
	ds_read_b128 v[114:117], v87 offset:32768
	ds_read_b128 v[118:121], v86
	ds_read_b128 v[122:125], v87 offset:36864
	ds_read_b128 v[150:153], v86 offset:4096
	s_waitcnt lgkmcnt(1)
	v_mfma_f32_32x32x16_bf16 v[48:63], v[114:117], v[118:121], v[48:63]
	v_mfma_f32_32x32x16_bf16 v[32:47], v[122:125], v[118:121], v[32:47]
	s_and_b32 m0, s32, 7
	s_lshl_b32 m0, m0, 11
	s_add_i32 m0, m0, 0x20400
	s_nop 0
	global_load_lds_dwordx4 v[168:169], off
	s_waitcnt lgkmcnt(0)
	v_mfma_f32_32x32x16_bf16 v[16:31], v[114:117], v[150:153], v[16:31]
	v_mfma_f32_32x32x16_bf16 v[0:15], v[122:125], v[150:153], v[0:15]
	ds_read_b128 v[114:117], v89 offset:32768
	ds_read_b128 v[118:121], v88
	ds_read_b128 v[122:125], v89 offset:36864
	ds_read_b128 v[154:157], v88 offset:4096
	s_waitcnt lgkmcnt(1)
	v_mfma_f32_32x32x16_bf16 v[48:63], v[114:117], v[118:121], v[48:63]
	v_mfma_f32_32x32x16_bf16 v[32:47], v[122:125], v[118:121], v[32:47]
	s_waitcnt vmcnt(6)
	s_waitcnt lgkmcnt(0)
	s_barrier
	s_waitcnt lgkmcnt(0)
	v_mfma_f32_32x32x16_bf16 v[16:31], v[114:117], v[154:157], v[16:31]
	v_lshl_add_u64 v[170:171], v[66:67], 0, s[30:31]
	s_nop 0
	v_lshl_add_u64 v[172:173], v[68:69], 0, s[30:31]
	s_nop 0
	s_nop 0
	s_nop 0
	v_lshl_add_u64 v[174:175], v[70:71], 0, s[30:31]
	s_nop 0
	v_mfma_f32_32x32x16_bf16 v[0:15], v[122:125], v[154:157], v[0:15]
	s_and_b32 m0, s32, 7
	s_lshl_b32 m0, m0, 12
	s_add_i32 m0, m0, 0x0
	s_nop 0
	global_load_lds_dwordx4 v[170:171], off
	s_nop 0
	v_lshl_add_u64 v[176:177], v[72:73], 0, s[30:31]
	s_nop 0
	s_nop 0
	s_nop 0
	v_lshl_add_u64 v[178:179], v[74:75], 0, s[30:31]
	s_nop 0
	s_nop 0
	s_nop 0
	v_lshl_add_u64 v[180:181], v[76:77], 0, s[30:31]
	s_nop 0
	s_mov_b64 s[30:31], 0x680
	s_nop 0
	ds_read_b128 v[114:117], v91
	ds_read_b128 v[118:121], v84 offset:49152
	ds_read_b128 v[122:125], v90
	ds_read_b128 v[150:153], v84 offset:53248
	s_waitcnt lgkmcnt(1)
	v_mfma_f32_32x32x16_bf16 v[48:63], v[114:117], v[118:121], v[48:63]
	s_nop 0
	v_mfma_f32_32x32x16_bf16 v[32:47], v[122:125], v[118:121], v[32:47]
	s_and_b32 m0, s32, 7
	s_lshl_b32 m0, m0, 12
	s_add_i32 m0, m0, 0x400
	s_nop 0
	global_load_lds_dwordx4 v[172:173], off
	s_waitcnt lgkmcnt(0)
	v_mfma_f32_32x32x16_bf16 v[16:31], v[114:117], v[150:153], v[16:31]
	v_mfma_f32_32x32x16_bf16 v[0:15], v[122:125], v[150:153], v[0:15]
	s_and_b32 m0, s32, 7
	s_lshl_b32 m0, m0, 12
	s_add_i32 m0, m0, 0x800
	s_nop 0
	global_load_lds_dwordx4 v[174:175], off
	ds_read_b128 v[114:117], v94
	ds_read_b128 v[118:121], v82 offset:49152
	ds_read_b128 v[122:125], v92
	ds_read_b128 v[154:157], v82 offset:53248
	s_waitcnt lgkmcnt(1)
	v_mfma_f32_32x32x16_bf16 v[48:63], v[114:117], v[118:121], v[48:63]
	v_mfma_f32_32x32x16_bf16 v[32:47], v[122:125], v[118:121], v[32:47]
	s_and_b32 m0, s32, 7
	s_lshl_b32 m0, m0, 12
	s_add_i32 m0, m0, 0xc00
	s_nop 0
	global_load_lds_dwordx4 v[176:177], off
	s_waitcnt lgkmcnt(0)
	v_mfma_f32_32x32x16_bf16 v[16:31], v[114:117], v[154:157], v[16:31]
	v_mfma_f32_32x32x16_bf16 v[0:15], v[122:125], v[154:157], v[0:15]
	s_and_b32 m0, s32, 7
	s_lshl_b32 m0, m0, 11
	s_add_i32 m0, m0, 0x8000
	s_nop 0
	global_load_lds_dwordx4 v[178:179], off
	ds_read_b128 v[114:117], v95
	ds_read_b128 v[118:121], v86 offset:49152
	ds_read_b128 v[122:125], v93
	ds_read_b128 v[150:153], v86 offset:53248
	s_waitcnt lgkmcnt(1)
	v_mfma_f32_32x32x16_bf16 v[48:63], v[114:117], v[118:121], v[48:63]
	v_mfma_f32_32x32x16_bf16 v[32:47], v[122:125], v[118:121], v[32:47]
	s_and_b32 m0, s32, 7
	s_lshl_b32 m0, m0, 11
	s_add_i32 m0, m0, 0x8400
	s_nop 0
	global_load_lds_dwordx4 v[180:181], off
	s_waitcnt lgkmcnt(0)
	v_mfma_f32_32x32x16_bf16 v[16:31], v[114:117], v[150:153], v[16:31]
	v_mfma_f32_32x32x16_bf16 v[0:15], v[122:125], v[150:153], v[0:15]
	ds_read_b128 v[114:117], v97
	ds_read_b128 v[118:121], v88 offset:49152
	ds_read_b128 v[122:125], v96
	ds_read_b128 v[154:157], v88 offset:53248
	s_waitcnt lgkmcnt(1)
	v_mfma_f32_32x32x16_bf16 v[48:63], v[114:117], v[118:121], v[48:63]
	v_mfma_f32_32x32x16_bf16 v[32:47], v[122:125], v[118:121], v[32:47]
	s_waitcnt vmcnt(6)
	s_waitcnt lgkmcnt(0)
	s_barrier
	s_waitcnt lgkmcnt(0)
	v_mfma_f32_32x32x16_bf16 v[16:31], v[114:117], v[154:157], v[16:31]
	v_lshl_add_u64 v[158:159], v[66:67], 0, s[30:31]
	s_nop 0
	v_lshl_add_u64 v[160:161], v[68:69], 0, s[30:31]
	s_nop 0
	s_nop 0
	s_nop 0
	v_lshl_add_u64 v[162:163], v[70:71], 0, s[30:31]
	s_nop 0
	v_mfma_f32_32x32x16_bf16 v[0:15], v[122:125], v[154:157], v[0:15]
	s_and_b32 m0, s32, 7
	s_lshl_b32 m0, m0, 12
	s_add_i32 m0, m0, 0xc000
	s_nop 0
	global_load_lds_dwordx4 v[158:159], off
	s_nop 0
	v_lshl_add_u64 v[164:165], v[72:73], 0, s[30:31]
	s_nop 0
	s_nop 0
	s_nop 0
	v_lshl_add_u64 v[166:167], v[74:75], 0, s[30:31]
	s_nop 0
	s_nop 0
	s_nop 0
	v_lshl_add_u64 v[168:169], v[76:77], 0, s[30:31]
	s_nop 0
	s_mov_b64 s[30:31], 0x700
	s_nop 0
	ds_read_b128 v[114:117], v98
	ds_read_b128 v[118:121], v100
	ds_read_b128 v[122:125], v99
	ds_read_b128 v[150:153], v101
	s_waitcnt lgkmcnt(1)
	v_mfma_f32_32x32x16_bf16 v[48:63], v[114:117], v[118:121], v[48:63]
	s_nop 0
	v_mfma_f32_32x32x16_bf16 v[32:47], v[122:125], v[118:121], v[32:47]
	s_and_b32 m0, s32, 7
	s_lshl_b32 m0, m0, 12
	s_add_i32 m0, m0, 0xc400
	s_nop 0
	global_load_lds_dwordx4 v[160:161], off
	s_waitcnt lgkmcnt(0)
	v_mfma_f32_32x32x16_bf16 v[16:31], v[114:117], v[150:153], v[16:31]
	v_mfma_f32_32x32x16_bf16 v[0:15], v[122:125], v[150:153], v[0:15]
	s_and_b32 m0, s32, 7
	s_lshl_b32 m0, m0, 12
	s_add_i32 m0, m0, 0xc800
	s_nop 0
	global_load_lds_dwordx4 v[162:163], off
	ds_read_b128 v[114:117], v103
	ds_read_b128 v[118:121], v104
	ds_read_b128 v[122:125], v102
	ds_read_b128 v[154:157], v105
	s_waitcnt lgkmcnt(1)
	v_mfma_f32_32x32x16_bf16 v[48:63], v[114:117], v[118:121], v[48:63]
	v_mfma_f32_32x32x16_bf16 v[32:47], v[122:125], v[118:121], v[32:47]
	s_and_b32 m0, s32, 7
	s_lshl_b32 m0, m0, 12
	s_add_i32 m0, m0, 0xcc00
	s_nop 0
	global_load_lds_dwordx4 v[164:165], off
	s_waitcnt lgkmcnt(0)
	v_mfma_f32_32x32x16_bf16 v[16:31], v[114:117], v[154:157], v[16:31]
	v_mfma_f32_32x32x16_bf16 v[0:15], v[122:125], v[154:157], v[0:15]
	s_and_b32 m0, s32, 7
	s_lshl_b32 m0, m0, 11
	s_add_i32 m0, m0, 0x14000
	s_nop 0
	global_load_lds_dwordx4 v[166:167], off
	ds_read_b128 v[114:117], v107
	ds_read_b128 v[118:121], v108
	ds_read_b128 v[122:125], v106
	ds_read_b128 v[150:153], v109
	s_waitcnt lgkmcnt(1)
	v_mfma_f32_32x32x16_bf16 v[48:63], v[114:117], v[118:121], v[48:63]
	v_mfma_f32_32x32x16_bf16 v[32:47], v[122:125], v[118:121], v[32:47]
	s_and_b32 m0, s32, 7
	s_lshl_b32 m0, m0, 11
	s_add_i32 m0, m0, 0x14400
	s_nop 0
	global_load_lds_dwordx4 v[168:169], off
	s_waitcnt lgkmcnt(0)
	v_mfma_f32_32x32x16_bf16 v[16:31], v[114:117], v[150:153], v[16:31]
	v_mfma_f32_32x32x16_bf16 v[0:15], v[122:125], v[150:153], v[0:15]
	ds_read_b128 v[114:117], v111
	ds_read_b128 v[118:121], v112
	ds_read_b128 v[122:125], v110
	ds_read_b128 v[154:157], v113
	s_waitcnt lgkmcnt(1)
	v_mfma_f32_32x32x16_bf16 v[48:63], v[114:117], v[118:121], v[48:63]
	v_mfma_f32_32x32x16_bf16 v[32:47], v[122:125], v[118:121], v[32:47]
	s_waitcnt vmcnt(6)
	s_waitcnt lgkmcnt(0)
	s_barrier
	s_waitcnt lgkmcnt(0)
	v_mfma_f32_32x32x16_bf16 v[16:31], v[114:117], v[154:157], v[16:31]
	v_lshl_add_u64 v[170:171], v[66:67], 0, s[30:31]
	s_nop 0
	v_lshl_add_u64 v[172:173], v[68:69], 0, s[30:31]
	s_nop 0
	s_nop 0
	s_nop 0
	v_lshl_add_u64 v[174:175], v[70:71], 0, s[30:31]
	s_nop 0
	v_mfma_f32_32x32x16_bf16 v[0:15], v[122:125], v[154:157], v[0:15]
	s_and_b32 m0, s32, 7
	s_lshl_b32 m0, m0, 12
	s_add_i32 m0, m0, 0x18000
	s_nop 0
	global_load_lds_dwordx4 v[170:171], off
	s_nop 0
	v_lshl_add_u64 v[176:177], v[72:73], 0, s[30:31]
	s_nop 0
	s_nop 0
	s_nop 0
	v_lshl_add_u64 v[178:179], v[74:75], 0, s[30:31]
	s_nop 0
	s_nop 0
	s_nop 0
	v_lshl_add_u64 v[180:181], v[76:77], 0, s[30:31]
	s_nop 0
	s_mov_b64 s[30:31], 0x780
	s_nop 0
	ds_read_b128 v[114:117], v85 offset:32768
	ds_read_b128 v[118:121], v84
	ds_read_b128 v[122:125], v85 offset:36864
	ds_read_b128 v[150:153], v84 offset:4096
	s_waitcnt lgkmcnt(1)
	v_mfma_f32_32x32x16_bf16 v[48:63], v[114:117], v[118:121], v[48:63]
	v_lshl_add_u64 v[158:159], v[66:67], 0, s[30:31]
	s_nop 0
	v_mfma_f32_32x32x16_bf16 v[32:47], v[122:125], v[118:121], v[32:47]
	s_and_b32 m0, s32, 7
	s_lshl_b32 m0, m0, 12
	s_add_i32 m0, m0, 0x18400
	s_nop 0
	global_load_lds_dwordx4 v[172:173], off
	s_waitcnt lgkmcnt(0)
	v_mfma_f32_32x32x16_bf16 v[16:31], v[114:117], v[150:153], v[16:31]
	v_mfma_f32_32x32x16_bf16 v[0:15], v[122:125], v[150:153], v[0:15]
	s_and_b32 m0, s32, 7
	s_lshl_b32 m0, m0, 12
	s_add_i32 m0, m0, 0x18800
	s_nop 0
	global_load_lds_dwordx4 v[174:175], off
	ds_read_b128 v[114:117], v83 offset:32768
	ds_read_b128 v[118:121], v82
	ds_read_b128 v[122:125], v83 offset:36864
	ds_read_b128 v[154:157], v82 offset:4096
	s_waitcnt lgkmcnt(1)
	v_mfma_f32_32x32x16_bf16 v[48:63], v[114:117], v[118:121], v[48:63]
	v_mfma_f32_32x32x16_bf16 v[32:47], v[122:125], v[118:121], v[32:47]
	s_and_b32 m0, s32, 7
	s_lshl_b32 m0, m0, 12
	s_add_i32 m0, m0, 0x18c00
	s_nop 0
	global_load_lds_dwordx4 v[176:177], off
	s_waitcnt lgkmcnt(0)
	v_mfma_f32_32x32x16_bf16 v[16:31], v[114:117], v[154:157], v[16:31]
	v_mfma_f32_32x32x16_bf16 v[0:15], v[122:125], v[154:157], v[0:15]
	s_and_b32 m0, s32, 7
	s_lshl_b32 m0, m0, 11
	s_add_i32 m0, m0, 0x20000
	s_nop 0
	global_load_lds_dwordx4 v[178:179], off
	ds_read_b128 v[114:117], v87 offset:32768
	ds_read_b128 v[118:121], v86
	ds_read_b128 v[122:125], v87 offset:36864
	ds_read_b128 v[150:153], v86 offset:4096
	s_waitcnt lgkmcnt(1)
	v_mfma_f32_32x32x16_bf16 v[48:63], v[114:117], v[118:121], v[48:63]
	v_mfma_f32_32x32x16_bf16 v[32:47], v[122:125], v[118:121], v[32:47]
	s_and_b32 m0, s32, 7
	s_lshl_b32 m0, m0, 11
	s_add_i32 m0, m0, 0x20400
	s_nop 0
	global_load_lds_dwordx4 v[180:181], off
	s_waitcnt lgkmcnt(0)
	v_mfma_f32_32x32x16_bf16 v[16:31], v[114:117], v[150:153], v[16:31]
	v_mfma_f32_32x32x16_bf16 v[0:15], v[122:125], v[150:153], v[0:15]
	ds_read_b128 v[114:117], v89 offset:32768
	ds_read_b128 v[118:121], v88
	ds_read_b128 v[122:125], v89 offset:36864
	ds_read_b128 v[154:157], v88 offset:4096
	s_waitcnt lgkmcnt(1)
	v_mfma_f32_32x32x16_bf16 v[48:63], v[114:117], v[118:121], v[48:63]
	v_mfma_f32_32x32x16_bf16 v[32:47], v[122:125], v[118:121], v[32:47]
	s_waitcnt vmcnt(6)
	s_waitcnt lgkmcnt(0)
	s_barrier
	s_nop 0
	v_lshl_add_u64 v[160:161], v[68:69], 0, s[30:31]
	s_nop 0
	s_waitcnt lgkmcnt(0)
	v_mfma_f32_32x32x16_bf16 v[16:31], v[114:117], v[154:157], v[16:31]
	s_nop 0
	v_lshl_add_u64 v[162:163], v[70:71], 0, s[30:31]
	s_nop 0
	s_nop 0
	s_nop 0
	v_lshl_add_u64 v[164:165], v[72:73], 0, s[30:31]
	s_nop 0
	v_mfma_f32_32x32x16_bf16 v[0:15], v[122:125], v[154:157], v[0:15]
	s_and_b32 m0, s32, 7
	s_lshl_b32 m0, m0, 12
	s_add_i32 m0, m0, 0x0
	s_nop 0
	global_load_lds_dwordx4 v[158:159], off
	s_nop 0
	v_lshl_add_u64 v[166:167], v[74:75], 0, s[30:31]
	s_nop 0
	s_nop 0
	s_nop 0
	v_lshl_add_u64 v[168:169], v[76:77], 0, s[30:31]
	s_nop 0
	s_nop 0
	s_nop 0
	ds_read_b128 v[66:69], v91
	ds_read_b128 v[70:73], v84 offset:49152
	ds_read_b128 v[74:77], v90
	ds_read_b128 v[150:153], v84 offset:53248
	s_waitcnt lgkmcnt(1)
	v_mfma_f32_32x32x16_bf16 v[48:63], v[66:69], v[70:73], v[48:63]
	v_mfma_f32_32x32x16_bf16 v[32:47], v[74:77], v[70:73], v[32:47]
	s_and_b32 m0, s32, 7
	s_lshl_b32 m0, m0, 12
	s_add_i32 m0, m0, 0x400
	s_nop 0
	global_load_lds_dwordx4 v[160:161], off
	s_waitcnt lgkmcnt(0)
	v_mfma_f32_32x32x16_bf16 v[16:31], v[66:69], v[150:153], v[16:31]
	v_mfma_f32_32x32x16_bf16 v[0:15], v[74:77], v[150:153], v[0:15]
	s_and_b32 m0, s32, 7
	s_lshl_b32 m0, m0, 12
	s_add_i32 m0, m0, 0x800
	s_nop 0
	global_load_lds_dwordx4 v[162:163], off
	ds_read_b128 v[66:69], v94
	ds_read_b128 v[70:73], v82 offset:49152
	ds_read_b128 v[74:77], v92
	ds_read_b128 v[154:157], v82 offset:53248
	s_waitcnt lgkmcnt(1)
	v_mfma_f32_32x32x16_bf16 v[48:63], v[66:69], v[70:73], v[48:63]
	v_mfma_f32_32x32x16_bf16 v[32:47], v[74:77], v[70:73], v[32:47]
	s_and_b32 m0, s32, 7
	s_lshl_b32 m0, m0, 12
	s_add_i32 m0, m0, 0xc00
	s_nop 0
	global_load_lds_dwordx4 v[164:165], off
	s_waitcnt lgkmcnt(0)
	v_mfma_f32_32x32x16_bf16 v[16:31], v[66:69], v[154:157], v[16:31]
	v_mfma_f32_32x32x16_bf16 v[0:15], v[74:77], v[154:157], v[0:15]
	s_and_b32 m0, s32, 7
	s_lshl_b32 m0, m0, 11
	s_add_i32 m0, m0, 0x8000
	s_nop 0
	global_load_lds_dwordx4 v[166:167], off
	ds_read_b128 v[66:69], v95
	ds_read_b128 v[70:73], v86 offset:49152
	ds_read_b128 v[74:77], v93
	ds_read_b128 v[150:153], v86 offset:53248
	s_waitcnt lgkmcnt(1)
	v_mfma_f32_32x32x16_bf16 v[48:63], v[66:69], v[70:73], v[48:63]
	v_mfma_f32_32x32x16_bf16 v[32:47], v[74:77], v[70:73], v[32:47]
	s_and_b32 m0, s32, 7
	s_lshl_b32 m0, m0, 11
	s_add_i32 m0, m0, 0x8400
	s_nop 0
	global_load_lds_dwordx4 v[168:169], off
	s_waitcnt lgkmcnt(0)
	v_mfma_f32_32x32x16_bf16 v[16:31], v[66:69], v[150:153], v[16:31]
	v_mfma_f32_32x32x16_bf16 v[0:15], v[74:77], v[150:153], v[0:15]
	ds_read_b128 v[66:69], v97
	ds_read_b128 v[70:73], v88 offset:49152
	ds_read_b128 v[74:77], v96
	ds_read_b128 v[154:157], v88 offset:53248
	s_waitcnt lgkmcnt(1)
	v_mfma_f32_32x32x16_bf16 v[48:63], v[66:69], v[70:73], v[48:63]
	v_mfma_f32_32x32x16_bf16 v[32:47], v[74:77], v[70:73], v[32:47]
	s_waitcnt vmcnt(6)
	s_waitcnt lgkmcnt(0)
	s_barrier
	s_waitcnt lgkmcnt(0)
	v_mfma_f32_32x32x16_bf16 v[16:31], v[66:69], v[154:157], v[16:31]
	v_lshrrev_b32_e32 v183, 7, v133
	v_and_b32_e32 v184, 31, v133
	v_lshl_or_b32 v183, v183, 6, v184
	v_add_u32_e32 v183, s2, v183
	v_lshlrev_b32_e32 v183, 2, v183
	global_load_dword v184, v183, s[76:77]
	global_load_dword v185, v183, s[76:77] offset:128
	v_mfma_f32_32x32x16_bf16 v[0:15], v[74:77], v[154:157], v[0:15]
	ds_read_b128 v[66:69], v98
	ds_read_b128 v[70:73], v100
	ds_read_b128 v[74:77], v99
	ds_read_b128 v[150:153], v101
	s_waitcnt lgkmcnt(1)
	v_mfma_f32_32x32x16_bf16 v[48:63], v[66:69], v[70:73], v[48:63]
	v_mfma_f32_32x32x16_bf16 v[32:47], v[74:77], v[70:73], v[32:47]
	s_waitcnt lgkmcnt(0)
	v_mfma_f32_32x32x16_bf16 v[16:31], v[66:69], v[150:153], v[16:31]
	v_mfma_f32_32x32x16_bf16 v[0:15], v[74:77], v[150:153], v[0:15]
	ds_read_b128 v[66:69], v103
	ds_read_b128 v[70:73], v104
	ds_read_b128 v[74:77], v102
	ds_read_b128 v[154:157], v105
	s_waitcnt lgkmcnt(1)
	v_mfma_f32_32x32x16_bf16 v[48:63], v[66:69], v[70:73], v[48:63]
	v_mfma_f32_32x32x16_bf16 v[32:47], v[74:77], v[70:73], v[32:47]
	s_waitcnt lgkmcnt(0)
	v_mfma_f32_32x32x16_bf16 v[16:31], v[66:69], v[154:157], v[16:31]
	v_mfma_f32_32x32x16_bf16 v[0:15], v[74:77], v[154:157], v[0:15]
	ds_read_b128 v[66:69], v107
	ds_read_b128 v[70:73], v108
	ds_read_b128 v[74:77], v106
	ds_read_b128 v[150:153], v109
	s_waitcnt lgkmcnt(1)
	v_mfma_f32_32x32x16_bf16 v[48:63], v[66:69], v[70:73], v[48:63]
	v_mfma_f32_32x32x16_bf16 v[32:47], v[74:77], v[70:73], v[32:47]
	s_waitcnt lgkmcnt(0)
	v_mfma_f32_32x32x16_bf16 v[16:31], v[66:69], v[150:153], v[16:31]
	v_mfma_f32_32x32x16_bf16 v[0:15], v[74:77], v[150:153], v[0:15]
	ds_read_b128 v[66:69], v111
	ds_read_b128 v[70:73], v112
	ds_read_b128 v[74:77], v110
	ds_read_b128 v[154:157], v113
	s_waitcnt lgkmcnt(1)
	v_mfma_f32_32x32x16_bf16 v[48:63], v[66:69], v[70:73], v[48:63]
	v_mfma_f32_32x32x16_bf16 v[32:47], v[74:77], v[70:73], v[32:47]
	s_waitcnt vmcnt(0)
	s_waitcnt lgkmcnt(0)
	s_barrier
	s_waitcnt lgkmcnt(0)
	v_mfma_f32_32x32x16_bf16 v[16:31], v[66:69], v[154:157], v[16:31]
	v_mfma_f32_32x32x16_bf16 v[0:15], v[74:77], v[154:157], v[0:15]
	ds_read_b128 v[66:69], v85 offset:32768
	ds_read_b128 v[70:73], v84
	ds_read_b128 v[74:77], v85 offset:36864
	ds_read_b128 v[150:153], v84 offset:4096
	s_waitcnt lgkmcnt(1)
	v_mfma_f32_32x32x16_bf16 v[48:63], v[66:69], v[70:73], v[48:63]
	v_mfma_f32_32x32x16_bf16 v[32:47], v[74:77], v[70:73], v[32:47]
	s_waitcnt lgkmcnt(0)
	v_mfma_f32_32x32x16_bf16 v[16:31], v[66:69], v[150:153], v[16:31]
	v_mfma_f32_32x32x16_bf16 v[0:15], v[74:77], v[150:153], v[0:15]
	ds_read_b128 v[66:69], v83 offset:32768
	ds_read_b128 v[70:73], v82
	ds_read_b128 v[74:77], v83 offset:36864
	ds_read_b128 v[154:157], v82 offset:4096
	s_waitcnt lgkmcnt(1)
	v_mfma_f32_32x32x16_bf16 v[48:63], v[66:69], v[70:73], v[48:63]
	v_mfma_f32_32x32x16_bf16 v[32:47], v[74:77], v[70:73], v[32:47]
	s_waitcnt lgkmcnt(0)
	v_mfma_f32_32x32x16_bf16 v[16:31], v[66:69], v[154:157], v[16:31]
	v_mfma_f32_32x32x16_bf16 v[0:15], v[74:77], v[154:157], v[0:15]
	ds_read_b128 v[66:69], v87 offset:32768
	ds_read_b128 v[70:73], v86
	ds_read_b128 v[74:77], v87 offset:36864
	ds_read_b128 v[150:153], v86 offset:4096
	s_waitcnt lgkmcnt(1)
	v_mfma_f32_32x32x16_bf16 v[48:63], v[66:69], v[70:73], v[48:63]
	v_mfma_f32_32x32x16_bf16 v[32:47], v[74:77], v[70:73], v[32:47]
	s_waitcnt lgkmcnt(0)
	v_mfma_f32_32x32x16_bf16 v[16:31], v[66:69], v[150:153], v[16:31]
	v_mfma_f32_32x32x16_bf16 v[0:15], v[74:77], v[150:153], v[0:15]
	ds_read_b128 v[70:73], v89 offset:32768
	ds_read_b128 v[66:69], v88
	ds_read_b128 v[74:77], v89 offset:36864
	ds_read_b128 v[82:85], v88 offset:4096
	s_waitcnt lgkmcnt(0)
	s_barrier
	s_waitcnt lgkmcnt(0)
	v_mfma_f32_32x32x16_bf16 v[48:63], v[70:73], v[66:69], v[48:63]
	v_mfma_f32_32x32x16_bf16 v[32:47], v[74:77], v[66:69], v[32:47]
	v_lshl_or_b32 v69, v80, 6, v81
	v_add_u32_e32 v66, s2, v69
	v_cmp_gt_i32_e32 vcc, s69, v66
	v_ashrrev_i32_e32 v67, 31, v66
	v_mov_b32_e32 v68, 0
	v_mfma_f32_32x32x16_bf16 v[16:31], v[70:73], v[82:85], v[16:31]
	v_mov_b32_e32 v70, 0
	v_mfma_f32_32x32x16_bf16 v[0:15], v[74:77], v[82:85], v[0:15]
	s_and_saveexec_b64 s[0:1], vcc
	s_cbranch_execz .LBB0_749
	v_lshl_add_u64 v[70:71], v[66:67], 2, s[76:77]
	v_mov_b32_e32 v70, v184
	v_fmamk_f32 v70, v70, 0x3a800000, v188
	v_mul_f32_e32 v71, 0x4b800000, v70
	v_cmp_gt_f32_e32 vcc, s82, v70
	s_nop 1
	v_cndmask_b32_e32 v70, v70, v71, vcc
	v_rsq_f32_e32 v70, v70
	s_nop 0
	v_mul_f32_e32 v71, 0x45800000, v70
	v_cndmask_b32_e32 v70, v70, v71, vcc
.LBB0_749:
	s_or_b64 exec, exec, s[0:1]
	s_movk_i32 s0, 0x110
	v_mul_f32_e32 v32, v32, v70
	v_mul_f32_e32 v33, v33, v70
	v_lshlrev_b32_e32 v64, 2, v64
	v_mul_lo_u32 v71, v69, s0
	v_mul_f32_e32 v48, v48, v70
	v_cvt_pk_bf16_f32 v32, v32, v33
	v_mul_f32_e32 v33, v34, v70
	v_mul_f32_e32 v34, v35, v70
	v_lshl_or_b32 v64, v79, 6, v64
	v_add_u32_e32 v71, 0, v71
	v_mul_f32_e32 v49, v49, v70
	v_cvt_pk_bf16_f32 v72, v48, v49
	v_mul_f32_e32 v48, v50, v70
	v_cvt_pk_bf16_f32 v33, v33, v34
	v_mul_f32_e32 v34, v36, v70
	v_mul_f32_e32 v35, v37, v70
	v_mul_f32_e32 v49, v51, v70
	v_cvt_pk_bf16_f32 v73, v48, v49
	v_lshl_add_u32 v48, v64, 1, v71
	v_cvt_pk_bf16_f32 v34, v34, v35
	v_mul_f32_e32 v35, v38, v70
	v_mul_f32_e32 v36, v39, v70
	v_cvt_pk_bf16_f32 v35, v35, v36
	ds_write2_b64 v48, v[32:33], v[34:35] offset0:8 offset1:10
	v_mul_f32_e32 v32, v40, v70
	v_mul_f32_e32 v33, v41, v70
	v_mul_f32_e32 v49, v52, v70
	v_mul_f32_e32 v50, v53, v70
	v_cvt_pk_bf16_f32 v32, v32, v33
	v_mul_f32_e32 v33, v42, v70
	v_mul_f32_e32 v34, v43, v70
	v_cvt_pk_bf16_f32 v50, v49, v50
	v_mul_f32_e32 v49, v54, v70
	v_mul_f32_e32 v51, v55, v70
	v_cvt_pk_bf16_f32 v33, v33, v34
	v_mul_f32_e32 v34, v44, v70
	v_mul_f32_e32 v35, v45, v70
	v_cvt_pk_bf16_f32 v51, v49, v51
	ds_write2_b64 v48, v[72:73], v[50:51] offset1:2
	v_mul_f32_e32 v49, v56, v70
	v_mul_f32_e32 v50, v57, v70
	v_cvt_pk_bf16_f32 v34, v34, v35
	v_mul_f32_e32 v35, v46, v70
	v_cvt_pk_bf16_f32 v50, v49, v50
	v_mul_f32_e32 v49, v58, v70
	v_mul_f32_e32 v51, v59, v70
	v_mul_f32_e32 v36, v47, v70
	v_cvt_pk_bf16_f32 v35, v35, v36
	ds_write2_b64 v48, v[32:33], v[34:35] offset0:12 offset1:14
	v_add3_u32 v32, s2, v69, 32
	v_cvt_pk_bf16_f32 v51, v49, v51
	v_mul_f32_e32 v49, v60, v70
	v_mul_f32_e32 v52, v61, v70
	v_mul_f32_e32 v53, v63, v70
	v_cmp_gt_i32_e32 vcc, s69, v32
	v_cvt_pk_bf16_f32 v52, v49, v52
	v_mul_f32_e32 v49, v62, v70
	v_cvt_pk_bf16_f32 v53, v49, v53
	ds_write2_b64 v48, v[50:51], v[52:53] offset0:4 offset1:6
	s_and_saveexec_b64 s[0:1], vcc
	s_cbranch_execz .LBB0_751
	v_lshl_add_u64 v[32:33], v[66:67], 2, s[76:77]
	v_mov_b32_e32 v32, v185
	v_fmamk_f32 v32, v32, 0x3a800000, v188
	v_mul_f32_e32 v33, 0x4b800000, v32
	v_cmp_gt_f32_e32 vcc, s82, v32
	s_nop 1
	v_cndmask_b32_e32 v32, v32, v33, vcc
	v_rsq_f32_e32 v32, v32
	s_nop 0
	v_mul_f32_e32 v33, 0x45800000, v32
	v_cndmask_b32_e32 v68, v32, v33, vcc
